# combined: ATTN software-pipelined tile loop + RC1 operand loads one unit ahead + P5 epilogue row-sum cache (no wait on hit) + simplified grid barrier
# speedup vs baseline: 1.0192x; 1.0153x over previous
.LBB0_946:
	v_add_f32_e32 v16, v16, v17
	v_add_f32_e32 v180, v180, v181
	v_lshlrev_b32_e32 v3, 2, v176
	s_lshl_b32 s6, s93, 8
	s_add_i32 s6, s6, 0xc000
	v_add_f32_e32 v16, v16, v180
	v_add_u32_e32 v3, s6, v3
	v_lshrrev_b32_e32 v4, 5, v176
	v_lshl_add_u32 v4, v4, 4, s6
	ds_write_b32 v3, v16
	s_waitcnt lgkmcnt(0)
	ds_read2_b32 v[66:67], v4 offset0:0 offset1:32
	ds_read2_b32 v[68:69], v4 offset0:1 offset1:33
	ds_read2_b32 v[70:71], v4 offset0:2 offset1:34
	ds_read2_b32 v[72:73], v4 offset0:3 offset1:35
	ds_read2_b32 v[74:75], v4 offset0:8 offset1:40
	ds_read2_b32 v[76:77], v4 offset0:9 offset1:41
	ds_read2_b32 v[78:79], v4 offset0:10 offset1:42
	ds_read2_b32 v[80:81], v4 offset0:11 offset1:43
	ds_read2_b32 v[82:83], v4 offset0:16 offset1:48
	ds_read2_b32 v[84:85], v4 offset0:17 offset1:49
	ds_read2_b32 v[86:87], v4 offset0:18 offset1:50
	ds_read2_b32 v[88:89], v4 offset0:19 offset1:51
	ds_read2_b32 v[90:91], v4 offset0:24 offset1:56
	ds_read2_b32 v[92:93], v4 offset0:25 offset1:57
	ds_read2_b32 v[94:95], v4 offset0:26 offset1:58
	ds_read2_b32 v[96:97], v4 offset0:27 offset1:59
	s_waitcnt lgkmcnt(0)
	v_add_f32_e32 v50, v66, v67
	v_add_f32_e32 v51, v68, v69
	v_add_f32_e32 v52, v70, v71
	v_add_f32_e32 v53, v72, v73
	v_add_f32_e32 v54, v74, v75
	v_add_f32_e32 v55, v76, v77
	v_add_f32_e32 v56, v78, v79
	v_add_f32_e32 v57, v80, v81
	v_add_f32_e32 v58, v82, v83
	v_add_f32_e32 v59, v84, v85
	v_add_f32_e32 v60, v86, v87
	v_add_f32_e32 v61, v88, v89
	v_add_f32_e32 v62, v90, v91
	v_add_f32_e32 v63, v92, v93
	v_add_f32_e32 v64, v94, v95
	v_add_f32_e32 v65, v96, v97
	s_nop 2
	v_rcp_f32_e32 v3, v50
	v_rcp_f32_e32 v4, v51
	s_waitcnt vmcnt(0)
	v_rcp_f32_e32 v5, v52
	v_mul_f32_e32 v34, v3, v34
	v_mul_f32_e32 v3, v18, v3
	v_cvt_pk_bf16_f32 v3, v3, s0
	ds_write_b16 v143, v3 offset:51264
	v_mul_f32_e32 v3, v4, v35
	v_cvt_pk_bf16_f32 v3, v3, s0
	ds_write_b16 v143, v3 offset:51328
	v_mul_f32_e32 v3, v19, v4
	v_cvt_pk_bf16_f32 v3, v3, s0
	v_rcp_f32_e32 v6, v53
	ds_write_b16 v143, v3 offset:51392
	v_mul_f32_e32 v3, v5, v36
	v_cvt_pk_bf16_f32 v3, v3, s0
	ds_write_b16 v143, v3 offset:51456
	v_mul_f32_e32 v3, v20, v5
	v_cvt_pk_bf16_f32 v3, v3, s0
	v_rcp_f32_e32 v7, v54
	ds_write_b16 v143, v3 offset:51520
	v_mul_f32_e32 v3, v6, v37
	v_cvt_pk_bf16_f32 v3, v3, s0
	ds_write_b16 v143, v3 offset:51584
	v_mul_f32_e32 v3, v21, v6
	v_cvt_pk_bf16_f32 v3, v3, s0
	v_rcp_f32_e32 v8, v55
	ds_write_b16 v143, v3 offset:51648
	v_mul_f32_e32 v3, v7, v38
	v_cvt_pk_bf16_f32 v3, v3, s0
	ds_write_b16 v143, v3 offset:52224
	v_mul_f32_e32 v3, v22, v7
	v_cvt_pk_bf16_f32 v3, v3, s0
	v_rcp_f32_e32 v9, v56
	ds_write_b16 v143, v3 offset:52288
	v_mul_f32_e32 v3, v8, v39
	v_cvt_pk_bf16_f32 v3, v3, s0
	ds_write_b16 v143, v3 offset:52352
	v_mul_f32_e32 v3, v23, v8
	v_cvt_pk_bf16_f32 v3, v3, s0
	v_rcp_f32_e32 v10, v57
	ds_write_b16 v143, v3 offset:52416
	v_mul_f32_e32 v3, v9, v40
	v_cvt_pk_bf16_f32 v3, v3, s0
	ds_write_b16 v143, v3 offset:52480
	v_mul_f32_e32 v3, v24, v9
	v_cvt_pk_bf16_f32 v3, v3, s0
	v_rcp_f32_e32 v11, v58
	ds_write_b16 v143, v3 offset:52544
	v_mul_f32_e32 v3, v10, v41
	v_cvt_pk_bf16_f32 v3, v3, s0
	ds_write_b16 v143, v3 offset:52608
	v_mul_f32_e32 v3, v25, v10
	v_cvt_pk_bf16_f32 v3, v3, s0
	v_rcp_f32_e32 v12, v59
	ds_write_b16 v143, v3 offset:52672
	v_mul_f32_e32 v3, v11, v42
	v_cvt_pk_bf16_f32 v3, v3, s0
	ds_write_b16 v143, v3 offset:53248
	v_mul_f32_e32 v3, v26, v11
	v_cvt_pk_bf16_f32 v3, v3, s0
	v_rcp_f32_e32 v13, v60
	ds_write_b16 v143, v3 offset:53312
	v_mul_f32_e32 v3, v12, v43
	v_cvt_pk_bf16_f32 v3, v3, s0
	ds_write_b16 v143, v3 offset:53376
	v_mul_f32_e32 v3, v27, v12
	v_cvt_pk_bf16_f32 v3, v3, s0
	v_rcp_f32_e32 v14, v61
	ds_write_b16 v143, v3 offset:53440
	v_mul_f32_e32 v3, v13, v44
	v_cvt_pk_bf16_f32 v3, v3, s0
	ds_write_b16 v143, v3 offset:53504
	v_mul_f32_e32 v3, v28, v13
	v_cvt_pk_bf16_f32 v3, v3, s0
	v_rcp_f32_e32 v15, v62
	ds_write_b16 v143, v3 offset:53568
	v_mul_f32_e32 v3, v14, v45
	v_cvt_pk_bf16_f32 v3, v3, s0
	ds_write_b16 v143, v3 offset:53632
	v_mul_f32_e32 v3, v29, v14
	v_cvt_pk_bf16_f32 v3, v3, s0
	v_rcp_f32_e32 v16, v63
	ds_write_b16 v143, v3 offset:53696
	v_mul_f32_e32 v3, v15, v46
	v_cvt_pk_bf16_f32 v3, v3, s0
	ds_write_b16 v143, v3 offset:54272
	v_mul_f32_e32 v3, v30, v15
	v_cvt_pk_bf16_f32 v3, v3, s0
	v_rcp_f32_e32 v17, v64
	ds_write_b16 v143, v3 offset:54336
	v_mul_f32_e32 v3, v16, v47
	v_cvt_pk_bf16_f32 v3, v3, s0
	ds_write_b16 v143, v3 offset:54400
	v_mul_f32_e32 v3, v31, v16
	v_cvt_pk_bf16_f32 v3, v3, s0
	v_rcp_f32_e32 v50, v65
	ds_write_b16 v143, v3 offset:54464
	v_mul_f32_e32 v3, v17, v48
	v_cvt_pk_bf16_f32 v3, v3, s0
	ds_write_b16 v143, v3 offset:54528
	v_mul_f32_e32 v3, v32, v17
	v_cvt_pk_bf16_f32 v3, v3, s0
	ds_write_b16 v143, v3 offset:54592
	v_mul_f32_e32 v3, v50, v49
	v_cvt_pk_bf16_f32 v3, v3, s0
	ds_write_b16 v143, v3 offset:54656
	v_mul_f32_e32 v3, v33, v50
	v_cvt_pk_bf16_f32 v34, v34, s0
	v_cvt_pk_bf16_f32 v3, v3, s0
	ds_write_b16 v143, v34 offset:51200
	ds_write_b16 v143, v3 offset:54720
	s_waitcnt lgkmcnt(0)
	ds_read_b128 v[4:7], v144 offset:51200
	ds_read_b128 v[8:11], v145 offset:51200
	s_lshl_b64 s[6:7], s[12:13], 11
	v_lshl_add_u64 v[16:17], v[126:127], 0, s[6:7]
	v_lshl_add_u64 v[12:13], v[16:17], 0, v[128:129]
	s_waitcnt lgkmcnt(1)
	global_store_dwordx4 v[12:13], v[4:7], off
	ds_read_b128 v[4:7], v146 offset:51200
	ds_read_b128 v[12:15], v147 offset:51200
	v_lshl_add_u64 v[18:19], v[16:17], 0, v[130:131]
	s_waitcnt lgkmcnt(2)
	global_store_dwordx4 v[18:19], v[8:11], off
	s_add_i32 s26, s26, 1
	s_cmp_eq_u32 s26, 4
	v_lshl_add_u64 v[8:9], v[16:17], 0, v[132:133]
	s_waitcnt lgkmcnt(1)
	global_store_dwordx4 v[8:9], v[4:7], off
	s_nop 1
	v_lshl_add_u64 v[4:5], v[16:17], 0, v[134:135]
	s_waitcnt lgkmcnt(0)
	global_store_dwordx4 v[4:5], v[12:15], off
	s_waitcnt lgkmcnt(0)
	s_cbranch_scc1 .LBB0_958

.LBB0_952:
	s_lshl_b32 s6, s5, 8
	s_add_i32 s14, s6, s16
	s_add_u32 s12, s8, s14
	s_addc_u32 s13, s9, 0
	s_lshl_b64 s[6:7], s[12:13], 10
	v_lshl_add_u64 v[4:5], v[114:115], 0, s[6:7]
	s_mov_b32 s15, s11
	global_load_dwordx4 v[98:101], v[4:5], off offset:32
	global_load_dwordx4 v[102:105], v[4:5], off offset:64
	global_load_dwordx4 v[106:109], v[4:5], off offset:96
	v_lshl_add_u64 v[136:137], s[14:15], 3, v[120:121]
	global_load_dwordx4 v[110:113], v[4:5], off
	global_load_dwordx2 v[138:139], v[136:137], off
	s_mov_b64 s[36:37], 0x8000
	v_lshl_add_u64 v[150:151], v[136:137], 0, s[36:37]
	global_load_dwordx2 v[180:181], v[150:151], off
	s_waitcnt lgkmcnt(0)
	s_barrier
	s_mov_b32 m0, s21
	global_load_lds_dwordx4 v[116:117], off
	s_mov_b32 m0, s22
	global_load_lds_dwordx4 v[118:119], off
	v_mov_b32_e32 v16, v2
	s_mov_b32 m0, s23
	global_load_lds_dwordx4 v[122:123], off
	s_mov_b32 m0, s24
	global_load_lds_dwordx4 v[124:125], off
	s_waitcnt vmcnt(2)
	v_mov_b32_e32 v17, v2
	s_lshl_b32 s6, s5, 2
	s_lshl_b32 s30, s5, 10
	v_mov_b32_e32 v3, v2
	v_mov_b32_e32 v4, v2
	v_mov_b32_e32 v5, v2
	v_mov_b32_e32 v6, v2
	v_mov_b32_e32 v7, v2
	v_mov_b32_e32 v8, v2
	v_mov_b32_e32 v9, v2
	v_mov_b32_e32 v10, v2
	v_mov_b32_e32 v11, v2
	v_mov_b32_e32 v12, v2
	v_mov_b32_e32 v13, v2
	v_mov_b32_e32 v14, v2
	v_mov_b32_e32 v15, v2
	v_mov_b64_e32 v[48:49], v[16:17]
	v_mov_b64_e32 v[32:33], v[16:17]
	v_mov_b64_e32 v[64:65], v[16:17]
	s_mov_b32 s15, 2
	s_add_i32 s27, s6, 4
	s_lshr_b32 s28, s14, 6
	s_or_b32 s29, s6, 3
	v_add_u32_e32 v148, s30, v142
	s_addk_i32 s30, 0x400
	s_mov_b32 s31, 0
	s_movk_i32 s33, 0xaf
	v_mov_b64_e32 v[46:47], v[14:15]
	v_mov_b64_e32 v[44:45], v[12:13]
	v_mov_b64_e32 v[42:43], v[10:11]
	v_mov_b64_e32 v[40:41], v[8:9]
	v_mov_b64_e32 v[38:39], v[6:7]
	v_mov_b64_e32 v[36:37], v[4:5]
	v_mov_b64_e32 v[34:35], v[2:3]
	v_mov_b64_e32 v[30:31], v[14:15]
	v_mov_b64_e32 v[28:29], v[12:13]
	v_mov_b64_e32 v[26:27], v[10:11]
	v_mov_b64_e32 v[24:25], v[8:9]
	v_mov_b64_e32 v[22:23], v[6:7]
	v_mov_b64_e32 v[20:21], v[4:5]
	v_mov_b64_e32 v[18:19], v[2:3]
	v_mov_b64_e32 v[62:63], v[14:15]
	v_mov_b64_e32 v[60:61], v[12:13]
	v_mov_b64_e32 v[58:59], v[10:11]
	v_mov_b64_e32 v[56:57], v[8:9]
	v_mov_b64_e32 v[54:55], v[6:7]
	v_mov_b64_e32 v[52:53], v[4:5]
	v_mov_b64_e32 v[50:51], v[2:3]
	s_mov_b32 s34, 0
	v_lshrrev_b32_e32 v3, v1, v138
	v_lshlrev_b32_e32 v3, 4, v3
	v_and_b32_e32 v177, 0xf0f0f0f0, v3
	v_lshrrev_b32_e32 v3, v1, v139
	v_lshlrev_b32_e32 v3, 4, v3
	v_and_b32_e32 v179, 0xf0f0f0f0, v3
	v_mov_b64_e32 v[138:139], v[180:181]
	v_mov_b32_e32 v180, 0
	v_mov_b32_e32 v181, 0
	v_mov_b32_e32 v16, 0
	v_mov_b32_e32 v17, 0
	s_branch .LBB0_955

.LBB0_955:
	s_add_i32 s35, s15, -2
	s_lshl_b32 s5, s34, 13
	s_cmp_lt_u32 s15, s27
	s_cselect_b32 s10, s15, s29
	s_lshl_b64 s[6:7], s[10:11], 16
	s_waitcnt vmcnt(0)
	v_lshl_add_u64 v[6:7], v[116:117], 0, s[6:7]
	v_lshl_add_u64 v[8:9], v[118:119], 0, s[6:7]
	s_add_i32 s6, s5, 0xffffe000
	s_cmp_lg_u32 s34, 0
	s_cselect_b32 s6, s6, 0x4000
	s_add_i32 s6, s20, s6
	s_waitcnt lgkmcnt(0)
	s_barrier
	s_add_i32 s7, s6, 0x6000
	s_mov_b32 m0, s6
	s_nop 0
	global_load_lds_dwordx4 v[6:7], off
	s_mov_b32 m0, s7
	s_nop 0
	global_load_lds_dwordx4 v[8:9], off
	s_add_i32 s36, s34, 1
	s_cmp_lg_u32 s34, 2
	s_cselect_b32 s36, s36, 0
	s_lshl_b32 s36, s36, 13
	s_cmp_gt_u32 s35, s28
	s_cbranch_scc1 .LBB0_954
	s_cmp_lg_u32 s35, 0
	s_cbranch_scc1 .Lsw_nf
	v_add_u32_e32 v149, s5, v140
	v_add_u32_sdwa v230, v177, s25 dst_sel:DWORD dst_unused:UNUSED_PAD src0_sel:BYTE_0 src1_sel:DWORD
	v_add_u32_sdwa v231, v177, s25 dst_sel:DWORD dst_unused:UNUSED_PAD src0_sel:BYTE_1 src1_sel:DWORD
	v_add_u32_sdwa v232, v177, s25 dst_sel:DWORD dst_unused:UNUSED_PAD src0_sel:BYTE_2 src1_sel:DWORD
	v_add_u32_sdwa v233, v177, s25 dst_sel:DWORD dst_unused:UNUSED_PAD src0_sel:BYTE_3 src1_sel:DWORD
	v_add_u32_sdwa v234, v179, s25 dst_sel:DWORD dst_unused:UNUSED_PAD src0_sel:BYTE_0 src1_sel:DWORD
	v_add_u32_sdwa v235, v179, s25 dst_sel:DWORD dst_unused:UNUSED_PAD src0_sel:BYTE_1 src1_sel:DWORD
	v_add_u32_sdwa v236, v179, s25 dst_sel:DWORD dst_unused:UNUSED_PAD src0_sel:BYTE_2 src1_sel:DWORD
	v_add_u32_sdwa v237, v179, s25 dst_sel:DWORD dst_unused:UNUSED_PAD src0_sel:BYTE_3 src1_sel:DWORD
	ds_read_b128 v[66:69], v230
	ds_read_b128 v[70:73], v231
	ds_read_b128 v[74:77], v232
	ds_read_b128 v[78:81], v233
	ds_read_b128 v[214:217], v149
	ds_read_b128 v[218:221], v149 offset:2048
	ds_read_b128 v[222:225], v149 offset:4096
	ds_read_b128 v[226:229], v149 offset:6144
	s_waitcnt lgkmcnt(3)
	v_mfma_f32_32x32x16_bf16 v[66:81], v[214:217], v[110:113], v[66:81]
	s_waitcnt lgkmcnt(2)
	v_mfma_f32_32x32x16_bf16 v[66:81], v[218:221], v[98:101], v[66:81]
	s_waitcnt lgkmcnt(1)
	v_mfma_f32_32x32x16_bf16 v[66:81], v[222:225], v[102:105], v[66:81]
	s_waitcnt lgkmcnt(0)
	v_mfma_f32_32x32x16_bf16 v[66:81], v[226:229], v[106:109], v[66:81]
	ds_read_b128 v[82:85], v234
	ds_read_b128 v[86:89], v235
	ds_read_b128 v[90:93], v236
	ds_read_b128 v[94:97], v237
	ds_read_b128 v[214:217], v149 offset:512
	ds_read_b128 v[218:221], v149 offset:2560
	ds_read_b128 v[222:225], v149 offset:4608
	ds_read_b128 v[226:229], v149 offset:6656
	s_waitcnt lgkmcnt(3)
	v_mfma_f32_32x32x16_bf16 v[82:97], v[214:217], v[110:113], v[82:97]
	s_waitcnt lgkmcnt(2)
	v_mfma_f32_32x32x16_bf16 v[82:97], v[218:221], v[98:101], v[82:97]
	s_waitcnt lgkmcnt(1)
	v_mfma_f32_32x32x16_bf16 v[82:97], v[222:225], v[102:105], v[82:97]
	s_waitcnt lgkmcnt(0)
	v_mfma_f32_32x32x16_bf16 v[82:97], v[226:229], v[106:109], v[82:97]
.Lsw_nf:
	s_cmp_ge_u32 s35, s28
	s_cbranch_scc1 .Lsw_nomask
	v_lshrrev_b32_e32 v3, v1, v138
	v_lshlrev_b32_e32 v3, 4, v3
	v_and_b32_e32 v177, 0xf0f0f0f0, v3
	v_lshrrev_b32_e32 v3, v1, v139
	v_lshlrev_b32_e32 v3, 4, v3
	v_and_b32_e32 v179, 0xf0f0f0f0, v3
	s_min_u32 s6, s15, 63
	s_mov_b32 s7, 0
	s_lshl_b64 s[6:7], s[6:7], 15
	v_lshl_add_u64 v[6:7], v[136:137], 0, s[6:7]
	global_load_dwordx2 v[138:139], v[6:7], off
.Lsw_nomask:
	s_cmp_lt_u32 s33, s14
	s_cbranch_scc1 .Lsw_nobias
	v_add_u32_e32 v3, s31, v148
	v_add_u32_e32 v4, 0x149fc, v3
	v_add_u32_e32 v6, 0x1497c, v3
	v_add_u32_e32 v8, 0x149f4, v3
	ds_read2_b32 v[4:5], v4 offset1:1
	ds_read2_b32 v[6:7], v6 offset1:1
	ds_read2_b32 v[8:9], v8 offset1:1
	v_add_u32_e32 v10, 0x14974, v3
	v_add_u32_e32 v12, 0x14954, v3
	s_waitcnt lgkmcnt(2)
	v_pk_add_f32 v[66:67], v[66:67], v[4:5] op_sel:[0,1] op_sel_hi:[1,0]
	s_waitcnt lgkmcnt(1)
	v_pk_add_f32 v[82:83], v[82:83], v[6:7] op_sel:[0,1] op_sel_hi:[1,0]
	s_waitcnt lgkmcnt(0)
	v_pk_add_f32 v[68:69], v[68:69], v[8:9] op_sel:[0,1] op_sel_hi:[1,0]
	v_add_u32_e32 v4, 0x149dc, v3
	v_add_u32_e32 v6, 0x1495c, v3
	v_add_u32_e32 v8, 0x149d4, v3
	ds_read2_b32 v[10:11], v10 offset1:1
	ds_read2_b32 v[4:5], v4 offset1:1
	ds_read2_b32 v[6:7], v6 offset1:1
	ds_read2_b32 v[8:9], v8 offset1:1
	ds_read2_b32 v[12:13], v12 offset1:1
	s_waitcnt lgkmcnt(3)
	v_pk_add_f32 v[70:71], v[70:71], v[4:5] op_sel:[0,1] op_sel_hi:[1,0]
	s_waitcnt lgkmcnt(2)
	v_pk_add_f32 v[86:87], v[86:87], v[6:7] op_sel:[0,1] op_sel_hi:[1,0]
	s_waitcnt lgkmcnt(1)
	v_pk_add_f32 v[72:73], v[72:73], v[8:9] op_sel:[0,1] op_sel_hi:[1,0]
	v_add_u32_e32 v4, 0x149bc, v3
	v_add_u32_e32 v6, 0x1493c, v3
	v_add_u32_e32 v8, 0x149b4, v3
	ds_read2_b32 v[4:5], v4 offset1:1
	ds_read2_b32 v[6:7], v6 offset1:1
	ds_read2_b32 v[8:9], v8 offset1:1
	v_pk_add_f32 v[84:85], v[84:85], v[10:11] op_sel:[0,1] op_sel_hi:[1,0]
	v_add_u32_e32 v10, 0x14934, v3
	s_waitcnt lgkmcnt(2)
	v_pk_add_f32 v[74:75], v[74:75], v[4:5] op_sel:[0,1] op_sel_hi:[1,0]
	s_waitcnt lgkmcnt(1)
	v_pk_add_f32 v[90:91], v[90:91], v[6:7] op_sel:[0,1] op_sel_hi:[1,0]
	s_waitcnt lgkmcnt(0)
	v_pk_add_f32 v[76:77], v[76:77], v[8:9] op_sel:[0,1] op_sel_hi:[1,0]
	v_add_u32_e32 v4, 0x1499c, v3
	v_add_u32_e32 v6, 0x1491c, v3
	v_add_u32_e32 v8, 0x14994, v3
	v_pk_add_f32 v[88:89], v[88:89], v[12:13] op_sel:[0,1] op_sel_hi:[1,0]
	ds_read2_b32 v[10:11], v10 offset1:1
	v_add_u32_e32 v3, 0x14914, v3
	ds_read2_b32 v[4:5], v4 offset1:1
	ds_read2_b32 v[6:7], v6 offset1:1
	ds_read2_b32 v[8:9], v8 offset1:1
	ds_read2_b32 v[12:13], v3 offset1:1
	s_waitcnt lgkmcnt(3)
	v_pk_add_f32 v[78:79], v[78:79], v[4:5] op_sel:[0,1] op_sel_hi:[1,0]
	v_pk_add_f32 v[92:93], v[92:93], v[10:11] op_sel:[0,1] op_sel_hi:[1,0]
	s_waitcnt lgkmcnt(2)
	v_pk_add_f32 v[94:95], v[94:95], v[6:7] op_sel:[0,1] op_sel_hi:[1,0]
	s_waitcnt lgkmcnt(1)
	v_pk_add_f32 v[80:81], v[80:81], v[8:9] op_sel:[0,1] op_sel_hi:[1,0]
	s_waitcnt lgkmcnt(0)
	v_pk_add_f32 v[96:97], v[96:97], v[12:13] op_sel:[0,1] op_sel_hi:[1,0]
.Lsw_nobias:
	s_cmp_ge_u32 s35, s28
	s_cbranch_scc1 .Lsw_last
	v_add_u32_e32 v151, s36, v140
	v_add_u32_e32 v150, s5, v141
	v_add_u32_sdwa v230, v177, s25 dst_sel:DWORD dst_unused:UNUSED_PAD src0_sel:BYTE_0 src1_sel:DWORD
	v_add_u32_sdwa v231, v177, s25 dst_sel:DWORD dst_unused:UNUSED_PAD src0_sel:BYTE_1 src1_sel:DWORD
	v_add_u32_sdwa v232, v177, s25 dst_sel:DWORD dst_unused:UNUSED_PAD src0_sel:BYTE_2 src1_sel:DWORD
	v_add_u32_sdwa v233, v177, s25 dst_sel:DWORD dst_unused:UNUSED_PAD src0_sel:BYTE_3 src1_sel:DWORD
	v_add_u32_sdwa v234, v179, s25 dst_sel:DWORD dst_unused:UNUSED_PAD src0_sel:BYTE_0 src1_sel:DWORD
	v_add_u32_sdwa v235, v179, s25 dst_sel:DWORD dst_unused:UNUSED_PAD src0_sel:BYTE_1 src1_sel:DWORD
	v_add_u32_sdwa v236, v179, s25 dst_sel:DWORD dst_unused:UNUSED_PAD src0_sel:BYTE_2 src1_sel:DWORD
	v_add_u32_sdwa v237, v179, s25 dst_sel:DWORD dst_unused:UNUSED_PAD src0_sel:BYTE_3 src1_sel:DWORD
	ds_read_b128 v[182:185], v230
	ds_read_b128 v[186:189], v231
	ds_read_b128 v[190:193], v232
	ds_read_b128 v[194:197], v233
	ds_read_b128 v[214:217], v151
	ds_read_b128 v[218:221], v151 offset:2048
	ds_read_b128 v[222:225], v151 offset:4096
	ds_read_b128 v[226:229], v151 offset:6144
	v_exp_f32_e32 v66, v66
	v_exp_f32_e32 v67, v67
	v_exp_f32_e32 v68, v68
	v_exp_f32_e32 v69, v69
	s_waitcnt lgkmcnt(3)
	v_mfma_f32_32x32x16_bf16 v[182:197], v[214:217], v[110:113], v[182:197]
	v_exp_f32_e32 v70, v70
	v_exp_f32_e32 v71, v71
	v_exp_f32_e32 v72, v72
	v_exp_f32_e32 v73, v73
	s_waitcnt lgkmcnt(2)
	v_mfma_f32_32x32x16_bf16 v[182:197], v[218:221], v[98:101], v[182:197]
	v_exp_f32_e32 v74, v74
	v_exp_f32_e32 v75, v75
	v_exp_f32_e32 v76, v76
	v_exp_f32_e32 v77, v77
	s_waitcnt lgkmcnt(1)
	v_mfma_f32_32x32x16_bf16 v[182:197], v[222:225], v[102:105], v[182:197]
	v_exp_f32_e32 v78, v78
	v_exp_f32_e32 v79, v79
	v_exp_f32_e32 v80, v80
	v_exp_f32_e32 v81, v81
	s_waitcnt lgkmcnt(0)
	v_mfma_f32_32x32x16_bf16 v[182:197], v[226:229], v[106:109], v[182:197]
	ds_read_b128 v[198:201], v234
	ds_read_b128 v[202:205], v235
	ds_read_b128 v[206:209], v236
	ds_read_b128 v[210:213], v237
	ds_read_b128 v[214:217], v151 offset:512
	ds_read_b128 v[218:221], v151 offset:2560
	ds_read_b128 v[222:225], v151 offset:4608
	ds_read_b128 v[226:229], v151 offset:6656
	v_cvt_pk_bf16_f32 v4, v66, v67
	v_cvt_pk_bf16_f32 v5, v68, v69
	v_cvt_pk_bf16_f32 v6, v70, v71
	v_cvt_pk_bf16_f32 v7, v72, v73
	v_cvt_pk_bf16_f32 v8, v74, v75
	v_cvt_pk_bf16_f32 v9, v76, v77
	v_cvt_pk_bf16_f32 v10, v78, v79
	v_cvt_pk_bf16_f32 v11, v80, v81
	v_add_f32_e32 v16, v16, v66
	v_add_f32_e32 v17, v17, v67
	v_add_f32_e32 v180, v180, v68
	v_add_f32_e32 v181, v181, v69
	v_add_f32_e32 v16, v16, v70
	v_add_f32_e32 v17, v17, v71
	v_add_f32_e32 v180, v180, v72
	v_add_f32_e32 v181, v181, v73
	ds_read_b64_tr_b16 v[152:153], v150
	ds_read_b64_tr_b16 v[154:155], v150 offset:512
	ds_read_b64_tr_b16 v[156:157], v150 offset:1024
	ds_read_b64_tr_b16 v[158:159], v150 offset:1536
	ds_read_b64_tr_b16 v[160:161], v150 offset:2048
	ds_read_b64_tr_b16 v[162:163], v150 offset:2560
	ds_read_b64_tr_b16 v[164:165], v150 offset:3072
	ds_read_b64_tr_b16 v[166:167], v150 offset:3584
	s_waitcnt lgkmcnt(11)
	v_mfma_f32_32x32x16_bf16 v[198:213], v[214:217], v[110:113], v[198:213]
	ds_read_b64_tr_b16 v[168:169], v150 offset:4096
	ds_read_b64_tr_b16 v[170:171], v150 offset:4608
	ds_read_b64_tr_b16 v[172:173], v150 offset:5120
	ds_read_b64_tr_b16 v[174:175], v150 offset:5632
	ds_read_b64_tr_b16 v[248:249], v150 offset:6144
	ds_read_b64_tr_b16 v[250:251], v150 offset:6656
	ds_read_b64_tr_b16 v[252:253], v150 offset:7168
	ds_read_b64_tr_b16 v[254:255], v150 offset:7680
	s_waitcnt lgkmcnt(15)
	v_mfma_f32_32x32x16_bf16 v[198:213], v[218:221], v[98:101], v[198:213]
	v_add_f32_e32 v16, v16, v74
	v_add_f32_e32 v17, v17, v75
	v_add_f32_e32 v180, v180, v76
	v_add_f32_e32 v181, v181, v77
	v_mfma_f32_32x32x16_bf16 v[198:213], v[222:225], v[102:105], v[198:213]
	v_add_f32_e32 v16, v16, v78
	v_add_f32_e32 v17, v17, v79
	v_add_f32_e32 v180, v180, v80
	v_add_f32_e32 v181, v181, v81
	v_mfma_f32_32x32x16_bf16 v[198:213], v[226:229], v[106:109], v[198:213]
	s_waitcnt lgkmcnt(8)
	v_mfma_f32_32x32x16_bf16 v[34:49], v[4:7], v[152:155], v[34:49]
	v_exp_f32_e32 v82, v82
	v_exp_f32_e32 v83, v83
	v_exp_f32_e32 v84, v84
	v_exp_f32_e32 v85, v85
	s_waitcnt lgkmcnt(6)
	v_mfma_f32_32x32x16_bf16 v[18:33], v[4:7], v[168:171], v[18:33]
	v_exp_f32_e32 v86, v86
	v_exp_f32_e32 v87, v87
	v_exp_f32_e32 v88, v88
	v_exp_f32_e32 v89, v89
	v_mfma_f32_32x32x16_bf16 v[34:49], v[8:11], v[156:159], v[34:49]
	v_exp_f32_e32 v90, v90
	v_exp_f32_e32 v91, v91
	v_exp_f32_e32 v92, v92
	v_exp_f32_e32 v93, v93
	s_waitcnt lgkmcnt(4)
	v_mfma_f32_32x32x16_bf16 v[18:33], v[8:11], v[172:175], v[18:33]
	v_exp_f32_e32 v94, v94
	v_exp_f32_e32 v95, v95
	v_exp_f32_e32 v96, v96
	v_exp_f32_e32 v97, v97
	v_cvt_pk_bf16_f32 v12, v82, v83
	v_cvt_pk_bf16_f32 v13, v84, v85
	v_cvt_pk_bf16_f32 v14, v86, v87
	v_cvt_pk_bf16_f32 v15, v88, v89
	v_cvt_pk_bf16_f32 v240, v90, v91
	v_cvt_pk_bf16_f32 v241, v92, v93
	v_cvt_pk_bf16_f32 v242, v94, v95
	v_cvt_pk_bf16_f32 v243, v96, v97
	v_add_f32_e32 v16, v16, v82
	v_add_f32_e32 v17, v17, v83
	v_add_f32_e32 v180, v180, v84
	v_add_f32_e32 v181, v181, v85
	v_mfma_f32_32x32x16_bf16 v[34:49], v[12:15], v[160:163], v[34:49]
	v_add_f32_e32 v16, v16, v86
	v_add_f32_e32 v17, v17, v87
	v_add_f32_e32 v180, v180, v88
	v_add_f32_e32 v181, v181, v89
	v_add_f32_e32 v16, v16, v90
	v_add_f32_e32 v17, v17, v91
	v_mov_b64_e32 v[66:67], v[182:183]
	v_mov_b64_e32 v[68:69], v[184:185]
	s_waitcnt lgkmcnt(2)
	v_mfma_f32_32x32x16_bf16 v[18:33], v[12:15], v[248:251], v[18:33]
	v_add_f32_e32 v180, v180, v92
	v_add_f32_e32 v181, v181, v93
	v_add_f32_e32 v16, v16, v94
	v_add_f32_e32 v17, v17, v95
	v_add_f32_e32 v180, v180, v96
	v_add_f32_e32 v181, v181, v97
	v_mov_b64_e32 v[70:71], v[186:187]
	v_mov_b64_e32 v[72:73], v[188:189]
	v_mov_b64_e32 v[74:75], v[190:191]
	v_mfma_f32_32x32x16_bf16 v[34:49], v[240:243], v[164:167], v[34:49]
	v_mov_b64_e32 v[76:77], v[192:193]
	v_mov_b64_e32 v[78:79], v[194:195]
	v_mov_b64_e32 v[80:81], v[196:197]
	v_mov_b64_e32 v[82:83], v[198:199]
	v_mov_b64_e32 v[84:85], v[200:201]
	s_waitcnt lgkmcnt(0)
	v_mfma_f32_32x32x16_bf16 v[18:33], v[240:243], v[252:255], v[18:33]
	v_mov_b64_e32 v[86:87], v[202:203]
	v_mov_b64_e32 v[88:89], v[204:205]
	v_mov_b64_e32 v[90:91], v[206:207]
	v_mov_b64_e32 v[92:93], v[208:209]
	v_mov_b64_e32 v[94:95], v[210:211]
	v_mov_b64_e32 v[96:97], v[212:213]
	s_branch .LBB0_954
.Lsw_last:
	v_add_u32_e32 v150, s5, v141
	ds_read_b64_tr_b16 v[152:153], v150
	ds_read_b64_tr_b16 v[154:155], v150 offset:512
	ds_read_b64_tr_b16 v[156:157], v150 offset:1024
	ds_read_b64_tr_b16 v[158:159], v150 offset:1536
	ds_read_b64_tr_b16 v[160:161], v150 offset:2048
	ds_read_b64_tr_b16 v[162:163], v150 offset:2560
	ds_read_b64_tr_b16 v[164:165], v150 offset:3072
	ds_read_b64_tr_b16 v[166:167], v150 offset:3584
	ds_read_b64_tr_b16 v[168:169], v150 offset:4096
	ds_read_b64_tr_b16 v[170:171], v150 offset:4608
	ds_read_b64_tr_b16 v[172:173], v150 offset:5120
	ds_read_b64_tr_b16 v[174:175], v150 offset:5632
	ds_read_b64_tr_b16 v[248:249], v150 offset:6144
	ds_read_b64_tr_b16 v[250:251], v150 offset:6656
	ds_read_b64_tr_b16 v[252:253], v150 offset:7168
	ds_read_b64_tr_b16 v[254:255], v150 offset:7680
	v_exp_f32_e32 v66, v66
	v_exp_f32_e32 v67, v67
	v_exp_f32_e32 v68, v68
	v_exp_f32_e32 v69, v69
	v_exp_f32_e32 v70, v70
	v_exp_f32_e32 v71, v71
	v_exp_f32_e32 v72, v72
	v_exp_f32_e32 v73, v73
	v_exp_f32_e32 v74, v74
	v_exp_f32_e32 v75, v75
	v_exp_f32_e32 v76, v76
	v_exp_f32_e32 v77, v77
	v_exp_f32_e32 v78, v78
	v_exp_f32_e32 v79, v79
	v_exp_f32_e32 v80, v80
	v_exp_f32_e32 v81, v81
	v_cvt_pk_bf16_f32 v4, v66, v67
	v_cvt_pk_bf16_f32 v5, v68, v69
	v_cvt_pk_bf16_f32 v6, v70, v71
	v_cvt_pk_bf16_f32 v7, v72, v73
	v_cvt_pk_bf16_f32 v8, v74, v75
	v_cvt_pk_bf16_f32 v9, v76, v77
	v_cvt_pk_bf16_f32 v10, v78, v79
	v_cvt_pk_bf16_f32 v11, v80, v81
	v_add_f32_e32 v16, v16, v66
	v_add_f32_e32 v17, v17, v67
	v_add_f32_e32 v180, v180, v68
	v_add_f32_e32 v181, v181, v69
	v_add_f32_e32 v16, v16, v70
	v_add_f32_e32 v17, v17, v71
	v_add_f32_e32 v180, v180, v72
	v_add_f32_e32 v181, v181, v73
	v_add_f32_e32 v16, v16, v74
	v_add_f32_e32 v17, v17, v75
	v_add_f32_e32 v180, v180, v76
	v_add_f32_e32 v181, v181, v77
	v_add_f32_e32 v16, v16, v78
	v_add_f32_e32 v17, v17, v79
	v_add_f32_e32 v180, v180, v80
	v_add_f32_e32 v181, v181, v81
	s_waitcnt lgkmcnt(8)
	v_mfma_f32_32x32x16_bf16 v[34:49], v[4:7], v[152:155], v[34:49]
	v_exp_f32_e32 v82, v82
	v_exp_f32_e32 v83, v83
	v_exp_f32_e32 v84, v84
	v_exp_f32_e32 v85, v85
	s_waitcnt lgkmcnt(6)
	v_mfma_f32_32x32x16_bf16 v[18:33], v[4:7], v[168:171], v[18:33]
	v_exp_f32_e32 v86, v86
	v_exp_f32_e32 v87, v87
	v_exp_f32_e32 v88, v88
	v_exp_f32_e32 v89, v89
	v_mfma_f32_32x32x16_bf16 v[34:49], v[8:11], v[156:159], v[34:49]
	v_exp_f32_e32 v90, v90
	v_exp_f32_e32 v91, v91
	v_exp_f32_e32 v92, v92
	v_exp_f32_e32 v93, v93
	s_waitcnt lgkmcnt(4)
	v_mfma_f32_32x32x16_bf16 v[18:33], v[8:11], v[172:175], v[18:33]
	v_exp_f32_e32 v94, v94
	v_exp_f32_e32 v95, v95
	v_exp_f32_e32 v96, v96
	v_exp_f32_e32 v97, v97
	v_cvt_pk_bf16_f32 v12, v82, v83
	v_cvt_pk_bf16_f32 v13, v84, v85
	v_cvt_pk_bf16_f32 v14, v86, v87
	v_cvt_pk_bf16_f32 v15, v88, v89
	v_cvt_pk_bf16_f32 v240, v90, v91
	v_cvt_pk_bf16_f32 v241, v92, v93
	v_cvt_pk_bf16_f32 v242, v94, v95
	v_cvt_pk_bf16_f32 v243, v96, v97
	v_add_f32_e32 v16, v16, v82
	v_add_f32_e32 v17, v17, v83
	v_add_f32_e32 v180, v180, v84
	v_add_f32_e32 v181, v181, v85
	v_mfma_f32_32x32x16_bf16 v[34:49], v[12:15], v[160:163], v[34:49]
	v_add_f32_e32 v16, v16, v86
	v_add_f32_e32 v17, v17, v87
	v_add_f32_e32 v180, v180, v88
	v_add_f32_e32 v181, v181, v89
	v_add_f32_e32 v16, v16, v90
	v_add_f32_e32 v17, v17, v91
	s_waitcnt lgkmcnt(2)
	v_mfma_f32_32x32x16_bf16 v[18:33], v[12:15], v[248:251], v[18:33]
	v_add_f32_e32 v180, v180, v92
	v_add_f32_e32 v181, v181, v93
	v_add_f32_e32 v16, v16, v94
	v_add_f32_e32 v17, v17, v95
	v_add_f32_e32 v180, v180, v96
	v_add_f32_e32 v181, v181, v97
	v_mfma_f32_32x32x16_bf16 v[34:49], v[240:243], v[164:167], v[34:49]
	s_waitcnt lgkmcnt(0)
	v_mfma_f32_32x32x16_bf16 v[18:33], v[240:243], v[252:255], v[18:33]
	s_branch .LBB0_954

.LBB0_1033:
	v_writelane_b32 v238, s87, 46
	v_writelane_b32 v238, s86, 47
	s_or_b64 exec, exec, s[0:1]
	s_add_u32 s0, s80, 0xa900000
	s_addc_u32 s1, s81, 0
	s_ashr_i32 s4, s40, 5
	s_ashr_i32 s5, s4, 31
	s_lshl_b64 s[52:53], s[4:5], 12
	s_lshl_b32 s2, s40, 6
	s_and_b32 s2, s2, 0xc0
	v_or_b32_e32 v92, s52, v176
	v_or_b32_e32 v4, s2, v92
	v_mov_b32_e32 v5, s53
	v_mov_b32_e32 v89, 0
	v_lshlrev_b64 v[4:5], 11, v[4:5]
	v_lshl_add_u64 v[4:5], s[0:1], 0, v[4:5]
	v_lshlrev_b64 v[10:11], 2, v[88:89]
	s_mov_b32 s55, 0
	v_and_b32_e32 v109, 0xffffffc0, v2
	v_lshl_add_u64 v[2:3], v[4:5], 0, v[10:11]
	s_lshl_b32 s54, s93, 5
	v_lshl_add_u64 v[12:13], v[2:3], 0, s[54:55]
	global_load_dwordx4 v[2:5], v[12:13], off offset:16
	global_load_dwordx4 v[6:9], v[12:13], off
	v_lshlrev_b32_e32 v12, 4, v178
	v_mov_b32_e32 v13, v89
	v_lshl_add_u64 v[14:15], v[88:89], 1, s[80:81]
	v_lshl_add_u64 v[12:13], v[14:15], 0, v[12:13]
	s_mov_b64 s[4:5], 0xe900000
	v_lshl_add_u64 v[94:95], v[12:13], 0, s[4:5]
	s_mov_b64 s[4:5], 0x8400000
	v_lshl_add_u64 v[96:97], v[12:13], 0, s[4:5]
	v_mbcnt_lo_u32_b32 v13, -1, 0
	v_mbcnt_hi_u32_b32 v13, -1, v13
	v_and_b32_e32 v15, 64, v13
	v_xor_b32_e32 v14, 1, v13
	v_add_u32_e32 v15, 64, v15
	v_and_b32_e32 v104, 15, v0
	v_cmp_lt_i32_e32 vcc, v14, v15
	v_lshl_add_u64 v[10:11], s[0:1], 0, v[10:11]
	v_cmp_eq_u32_e64 s[0:1], 0, v104
	v_cndmask_b32_e32 v14, v13, v14, vcc
	v_lshlrev_b32_e32 v112, 2, v14
	v_xor_b32_e32 v14, 2, v13
	v_cndmask_b32_e64 v121, 0, 1.0, s[0:1]
	v_cmp_eq_u32_e64 s[0:1], 1, v104
	s_add_i32 s8, 0, 0x1e400
	v_cmp_lt_i32_e32 vcc, v14, v15
	v_readlane_b32 s9, v238, 38
	v_cndmask_b32_e64 v122, 0, 1.0, s[0:1]
	v_cmp_eq_u32_e64 s[0:1], 2, v104
	s_lshl_b32 s2, s93, 3
	s_add_i32 s4, s54, s8
	v_cndmask_b32_e32 v14, v13, v14, vcc
	s_bfe_u32 s35, s9, 0x20006
	v_cndmask_b32_e64 v123, 0, 1.0, s[0:1]
	v_cmp_eq_u32_e64 s[0:1], 3, v104
	v_lshlrev_b32_e32 v113, 2, v14
	v_xor_b32_e32 v14, 4, v13
	s_cmpk_gt_u32 s9, 0xff
	v_cndmask_b32_e64 v124, 0, 1.0, s[0:1]
	v_cmp_eq_u32_e64 s[0:1], 4, v104
	v_cmp_lt_i32_e32 vcc, v14, v15
	s_cselect_b64 s[56:57], -1, 0
	s_cmpk_lt_u32 s9, 0x100
	v_cndmask_b32_e64 v125, 0, 1.0, s[0:1]
	v_cmp_eq_u32_e64 s[0:1], 5, v104
	v_cndmask_b32_e32 v13, v13, v14, vcc
	s_cselect_b64 vcc, -1, 0
	v_cndmask_b32_e64 v126, 0, 1.0, s[0:1]
	v_cmp_eq_u32_e64 s[0:1], 6, v104
	s_and_b64 s[6:7], vcc, exec
	s_mov_b32 s7, 0x16800
	v_cndmask_b32_e64 v127, 0, 1.0, s[0:1]
	v_cmp_eq_u32_e64 s[0:1], 7, v104
	s_cselect_b32 s34, s7, 0x18c00
	s_mov_b32 s7, 0x1b000
	v_cndmask_b32_e64 v128, 0, 1.0, s[0:1]
	v_cmp_eq_u32_e64 s[0:1], 8, v104
	s_cselect_b32 s6, 0, 0x2400
	s_cselect_b32 s10, s7, 0x12000
	v_cndmask_b32_e64 v129, 0, 1.0, s[0:1]
	v_cmp_eq_u32_e64 s[0:1], 9, v104
	s_mov_b32 s7, 0xfc00
	s_cselect_b32 s37, s7, 0x14400
	v_cndmask_b32_e64 v130, 0, 1.0, s[0:1]
	v_cmp_eq_u32_e64 s[0:1], 10, v104
	s_add_i32 s87, s6, 0
	s_lshr_b32 s94, s9, 7
	s_lshl_b32 s6, s93, 1
	v_cndmask_b32_e64 v131, 0, 1.0, s[0:1]
	v_cmp_eq_u32_e64 s[0:1], 11, v104
	s_and_b32 s95, s6, 2
	s_lshl_b32 s6, s94, 4
	v_cndmask_b32_e64 v132, 0, 1.0, s[0:1]
	v_cmp_eq_u32_e64 s[0:1], 12, v104
	v_lshrrev_b32_e32 v108, 4, v176
	v_or_b32_e32 v21, s6, v104
	s_movk_i32 s96, 0x90
	v_cndmask_b32_e64 v133, 0, 1.0, s[0:1]
	v_cmp_eq_u32_e64 s[0:1], 13, v104
	v_lshlrev_b32_e32 v105, 2, v108
	v_mul_lo_u32 v21, v21, s96
	v_cndmask_b32_e64 v134, 0, 1.0, s[0:1]
	v_cmp_eq_u32_e64 s[0:1], 14, v104
	s_lshl_b32 s36, s35, 4
	s_add_i32 s97, 0, 0x1d400
	v_add_u32_e32 v118, 0, v21
	v_or_b32_e32 v21, s6, v105
	s_add_i32 s6, s93, -2
	v_cndmask_b32_e64 v135, 0, 1.0, s[0:1]
	v_cmp_eq_u32_e64 s[0:1], 15, v104
	s_cmp_lt_u32 s6, 4
	s_cselect_b64 s[58:59], -1, 0
	v_cndmask_b32_e64 v136, 0, 1.0, s[0:1]
	s_mov_b32 s0, s93
	v_writelane_b32 v238, s0, 48
	s_lshl_b32 s0, s0, 10
	s_and_b32 s0, s0, 0x7ffff000
	v_or_b32_e32 v16, s36, v104
	v_lshlrev_b32_e32 v19, 2, v104
	s_lshl_b32 s38, s6, 10
	s_add_i32 s0, s0, 0
	v_add_u32_e32 v20, s97, v19
	v_and_b32_e32 v106, 48, v0
	v_lshl_add_u64 v[98:99], v[10:11], 0, s[54:55]
	s_add_i32 s97, s97, s38
	s_add_i32 s93, s34, 0
	s_add_i32 s0, s0, 0x23700
	v_lshlrev_b32_e32 v10, 6, v16
	v_lshrrev_b32_e32 v90, 3, v0
	v_mul_u32_u24_e32 v17, 0x48, v16
	v_add_u32_e32 v11, s0, v10
	v_add_u32_e32 v16, s0, v106
	s_cmp_eq_u32 s94, 2
	s_mov_b32 s0, 0x6400000
	v_lshlrev_b32_e32 v114, 2, v13
	v_mul_u32_u24_e32 v13, 0x104, v90
	v_lshlrev_b32_e32 v14, 5, v178
	s_cselect_b32 s0, s0, 0x1db00000
	s_cmp_lg_u32 s94, 1
	v_add3_u32 v115, s8, v13, v14
	v_add_u32_e32 v22, s8, v19
	s_cselect_b32 s8, s0, 0x4400000
	s_cmpk_gt_u32 s9, 0x7f
	s_cselect_b64 s[60:61], -1, 0
	s_and_b64 s[0:1], s[60:61], exec
	v_or_b32_e32 v18, s36, v105
	s_cselect_b32 s0, s8, 0x2400000
	s_add_u32 s66, s80, s0
	v_cmp_lt_u32_e64 s[0:1], v104, v18
	v_or_b32_e32 v34, 2, v18
	s_movk_i32 s85, 0x48
	v_cndmask_b32_e64 v29, 0, 1, s[0:1]
	v_cmp_le_u32_e64 s[0:1], v104, v18
	s_addc_u32 s67, s81, 0
	s_cmp_eq_u32 s35, 0
	v_cndmask_b32_e64 v30, 0, 1, s[0:1]
	v_cmp_lt_u32_e64 s[0:1], v104, v34
	s_cselect_b64 s[8:9], -1, 0
	s_and_b64 s[68:69], vcc, s[8:9]
	v_cndmask_b32_e64 v35, 0, 1, s[0:1]
	v_cmp_le_u32_e64 s[0:1], v104, v34
	s_add_i32 s42, s10, 0
	s_cmp_eq_u32 s35, 1
	v_cndmask_b32_e64 v36, 0, 1, s[0:1]
	v_cndmask_b32_e32 v35, v36, v35, vcc
	v_mov_b32_e32 v36, 0x90
	v_mad_u32_u24 v36, v18, s85, v36
	v_or_b32_e32 v37, v36, v104
	v_lshlrev_b32_e32 v142, 1, v37
	v_or_b32_e32 v37, 3, v18
	v_cmp_lt_u32_e64 s[0:1], v104, v37
	v_or_b32_e32 v144, 16, v104
	v_cndmask_b32_e32 v29, v30, v29, vcc
	v_cndmask_b32_e64 v38, 0, 1, s[0:1]
	v_cmp_le_u32_e64 s[0:1], v104, v37
	v_mul_u32_u24_e32 v30, 0x48, v18
	v_or_b32_e32 v31, v30, v104
	v_cndmask_b32_e64 v39, 0, 1, s[0:1]
	s_cselect_b64 s[0:1], -1, 0
	s_and_b64 s[70:71], vcc, s[0:1]
	v_cmp_lt_u32_e64 s[0:1], v144, v18
	s_cmp_eq_u32 s35, 2
	v_lshlrev_b32_e32 v140, 1, v31
	v_cndmask_b32_e64 v41, 0, 1, s[0:1]
	v_cmp_le_u32_e64 s[0:1], v144, v18
	v_or_b32_e32 v31, 1, v18
	v_cndmask_b32_e32 v38, v39, v38, vcc
	v_cndmask_b32_e64 v42, 0, 1, s[0:1]
	v_cndmask_b32_e32 v41, v42, v41, vcc
	v_or_b32_e32 v42, v30, v144
	v_cmp_lt_u32_e64 s[0:1], v144, v34
	v_lshlrev_b32_e32 v145, 1, v42
	v_mov_b32_e32 v39, 0xd8
	v_cndmask_b32_e64 v42, 0, 1, s[0:1]
	v_cmp_le_u32_e64 s[0:1], v144, v34
	v_cndmask_b32_e32 v32, v31, v18, vcc
	v_mad_u32_u24 v33, v18, s85, s85
	v_cndmask_b32_e64 v43, 0, 1, s[0:1]
	v_cndmask_b32_e32 v42, v43, v42, vcc
	v_and_b32_e32 v42, 1, v42
	v_cmp_lt_u32_e64 s[0:1], v144, v37
	v_cmp_eq_u32_e64 s[20:21], 1, v42
	v_mad_u32_u24 v39, v18, s85, v39
	v_cndmask_b32_e64 v42, 0, 1, s[0:1]
	v_cmp_le_u32_e64 s[0:1], v144, v37
	v_and_b32_e32 v41, 1, v41
	v_cmp_eq_u32_e64 s[16:17], 1, v41
	v_cndmask_b32_e64 v43, 0, 1, s[0:1]
	v_cndmask_b32_e32 v42, v43, v42, vcc
	v_and_b32_e32 v42, 1, v42
	v_cmp_eq_u32_e64 s[22:23], 1, v42
	v_or_b32_e32 v42, 32, v104
	s_cselect_b64 s[0:1], -1, 0
	s_and_b64 s[72:73], vcc, s[0:1]
	v_cmp_lt_u32_e64 s[0:1], v42, v18
	s_cmp_eq_u32 s35, 3
	v_add_lshl_u32 v150, v30, v42, 1
	v_cndmask_b32_e64 v44, 0, 1, s[0:1]
	v_cmp_le_u32_e64 s[0:1], v42, v18
	v_cmp_gt_u32_e64 s[26:27], v42, v32
	v_add_lshl_u32 v151, v33, v42, 1
	v_cndmask_b32_e64 v45, 0, 1, s[0:1]
	v_cndmask_b32_e32 v44, v45, v44, vcc
	v_and_b32_e32 v44, 1, v44
	v_cmp_lt_u32_e64 s[0:1], v42, v34
	v_cmp_eq_u32_e64 s[24:25], 1, v44
	v_add_lshl_u32 v152, v36, v42, 1
	v_cndmask_b32_e64 v44, 0, 1, s[0:1]
	v_cmp_le_u32_e64 s[0:1], v42, v34
	v_add_lshl_u32 v153, v39, v42, 1
	v_lshlrev_b32_e32 v41, 6, v18
	v_cndmask_b32_e64 v45, 0, 1, s[0:1]
	v_cndmask_b32_e32 v44, v45, v44, vcc
	v_and_b32_e32 v44, 1, v44
	v_cmp_lt_u32_e64 s[0:1], v42, v37
	v_cmp_eq_u32_e64 s[28:29], 1, v44
	v_add_lshl_u32 v141, v33, v104, 1
	v_cndmask_b32_e64 v44, 0, 1, s[0:1]
	v_cmp_le_u32_e64 s[0:1], v42, v37
	v_or_b32_e32 v42, 48, v104
	v_add_lshl_u32 v154, v30, v42, 1
	v_cndmask_b32_e64 v45, 0, 1, s[0:1]
	v_cndmask_b32_e32 v44, v45, v44, vcc
	s_cselect_b64 s[0:1], -1, 0
	v_and_b32_e32 v44, 1, v44
	s_and_b64 s[74:75], vcc, s[0:1]
	v_cmp_lt_u32_e64 s[0:1], v42, v18
	v_cmp_eq_u32_e64 s[30:31], 1, v44
	v_add_lshl_u32 v146, v33, v144, 1
	v_cndmask_b32_e64 v44, 0, 1, s[0:1]
	v_cmp_le_u32_e64 s[0:1], v42, v18
	v_add_lshl_u32 v155, v33, v42, 1
	v_and_b32_e32 v35, 1, v35
	v_cndmask_b32_e64 v18, 0, 1, s[0:1]
	v_cmp_lt_u32_e64 s[0:1], v42, v34
	v_cmp_eq_u32_e64 s[12:13], 1, v35
	v_lshlrev_b32_e32 v35, 6, v34
	v_cndmask_b32_e64 v30, 0, 1, s[0:1]
	v_cmp_le_u32_e64 s[0:1], v42, v34
	s_add_i32 s51, s38, 0
	v_add_lshl_u32 v143, v39, v104, 1
	v_cndmask_b32_e64 v33, 0, 1, s[0:1]
	v_cmp_lt_u32_e64 s[0:1], v42, v37
	v_cndmask_b32_e32 v30, v33, v30, vcc
	v_add_lshl_u32 v149, v39, v144, 1
	v_cndmask_b32_e64 v33, 0, 1, s[0:1]
	v_cmp_le_u32_e64 s[0:1], v42, v37
	v_cndmask_b32_e32 v18, v18, v44, vcc
	v_add_lshl_u32 v157, v39, v42, 1
	v_cndmask_b32_e64 v34, 0, 1, s[0:1]
	s_or_b32 s0, s95, 1
	v_lshl_add_u32 v39, s95, 6, v22
	v_lshl_or_b32 v44, s0, 4, v104
	v_lshl_add_u32 v22, s0, 6, v22
	s_add_i32 s0, s51, 0x22700
	v_writelane_b32 v238, s0, 39
	s_add_i32 s0, s51, 0x22740
	v_writelane_b32 v238, s0, 43
	s_add_i32 s0, s51, 0x22780
	v_writelane_b32 v238, s0, 49
	s_add_i32 s0, s51, 0x227c0
	v_writelane_b32 v238, s0, 50
	s_add_i32 s0, s51, 0x22800
	v_writelane_b32 v238, s0, 51
	s_add_i32 s0, s51, 0x22840
	v_writelane_b32 v238, s0, 52
	s_add_i32 s0, s51, 0x22880
	v_writelane_b32 v238, s0, 53
	s_add_i32 s0, s51, 0x228c0
	v_writelane_b32 v238, s0, 54
	s_add_i32 s0, s51, 0x22900
	v_writelane_b32 v238, s0, 55
	s_add_i32 s0, s51, 0x22940
	v_writelane_b32 v238, s0, 56
	s_add_i32 s0, s51, 0x22980
	v_writelane_b32 v238, s0, 57
	v_mul_u32_u24_e32 v47, 0x410, v108
	s_lshl_b32 s0, s35, 6
	v_add3_u32 v159, v47, s0, v19
	s_lshl_b32 s0, s35, 5
	s_mov_b32 s46, s40
	s_movk_i32 s40, 0x240
	v_mov_b32_e32 v19, s0
	v_lshlrev_b32_e32 v158, 1, v104
	v_mad_u32_u24 v19, v108, s40, v19
	v_add_u32_e32 v161, 0x16800, v1
	v_or_b32_e32 v1, v19, v158
	s_movk_i32 s39, 0x120
	v_add_u32_e32 v162, 0x90, v1
	v_mov_b32_e32 v1, s36
	v_lshrrev_b32_e32 v14, 6, v0
	v_mad_u32_u24 v1, v108, s39, v1
	v_bitop3_b32 v14, v14, v0, 7 bitop3:0x78
	v_lshlrev_b32_e32 v86, 3, v108
	v_or_b32_e32 v1, v1, v104
	v_lshlrev_b32_e32 v14, 3, v14
	v_bfe_u32 v15, v0, 3, 3
	v_lshlrev_b32_e32 v138, 6, v104
	v_mul_u32_u24_e32 v23, 0x240, v178
	v_cndmask_b32_e32 v33, v34, v33, vcc
	v_lshl_or_b32 v34, s95, 4, v104
	v_lshlrev_b32_e32 v163, 1, v1
	v_or_b32_e32 v1, s34, v86
	s_movk_i32 s33, 0x104
	v_mov_b32_e32 v12, s4
	v_or3_b32 v14, v14, v15, v23
	v_mul_u32_u24_e32 v107, 0x48, v104
	v_and_b32_e32 v38, 1, v38
	v_add_lshl_u32 v147, v36, v144, 1
	v_add_lshl_u32 v156, v36, v42, 1
	v_lshrrev_b32_e32 v36, 3, v34
	v_lshrrev_b32_e32 v45, 3, v44
	v_lshl_add_u32 v164, v17, 1, v1
	v_or_b32_e32 v1, v138, v106
	v_lshlrev_b32_e32 v110, 3, v178
	v_mad_u32_u24 v111, v176, s33, v12
	v_mul_u32_u24_e32 v12, 0xd0, v178
	v_mul_u32_u24_e32 v13, 0x48, v90
	v_lshlrev_b32_e32 v139, 1, v14
	v_add_lshl_u32 v28, v107, v86, 1
	v_and_b32_e32 v29, 1, v29
	v_cmp_eq_u32_e64 s[14:15], 1, v38
	v_lshlrev_b32_e32 v38, 6, v37
	v_xor_b32_e32 v37, v36, v108
	v_bitop3_b32 v36, v36, v108, 4 bitop3:0x1e
	v_xor_b32_e32 v46, v45, v108
	v_bitop3_b32 v45, v45, v108, 4 bitop3:0x1e
	v_add_u32_e32 v165, 0x22700, v1
	v_and_b32_e32 v1, 48, v176
	v_add_lshl_u32 v13, v13, v110, 1
	v_or_b32_e32 v119, 4, v108
	v_add_u32_e32 v14, 0x90, v139
	v_add_u32_e32 v15, 0x120, v139
	v_add_u32_e32 v23, 0x1b0, v139
	v_add_u32_e32 v24, 0x240, v139
	v_add_u32_e32 v25, 0x2d0, v139
	v_add_u32_e32 v26, 0x360, v139
	v_add_u32_e32 v27, 0x3f0, v139
	v_add_u32_e32 v148, 0, v28
	v_cmp_eq_u32_e64 s[8:9], 1, v29
	v_lshlrev_b32_e32 v29, 8, v108
	v_lshlrev_b32_e32 v31, 6, v31
	v_add_u32_e32 v40, 0x900, v28
	v_add_u32_e32 v43, 0x1200, v28
	v_add_u32_e32 v28, 0x1b00, v28
	v_and_b32_e32 v18, 1, v18
	v_and_b32_e32 v30, 1, v30
	v_and_b32_e32 v33, 1, v33
	v_mad_u32_u24 v34, v34, s96, 0
	v_lshlrev_b32_e32 v37, 4, v37
	v_lshlrev_b32_e32 v36, 4, v36
	v_mul_lo_u32 v21, v21, s33
	v_mad_u32_u24 v44, v44, s96, 0
	v_lshlrev_b32_e32 v46, 4, v46
	v_lshlrev_b32_e32 v45, 4, v45
	s_mov_b32 s0, s46
	v_mad_u32_u24 v166, v104, s96, v1
	v_add_u32_e32 v1, 0, v12
	v_mov_b32_e32 v91, v89
	v_mov_b32_e32 v93, s53
	v_cmp_eq_u32_e64 s[44:45], 63, v176
	v_cmp_lt_u32_e64 s[4:5], 7, v0
	v_add_u32_e32 v116, 0xfffffefc, v115
	v_add_lshl_u32 v117, v17, v86, 1
	v_lshlrev_b32_e32 v120, 4, v119
	v_cmp_gt_u32_e64 s[6:7], 16, v176
	v_bfe_u32 v137, v176, 4, 1
	v_and_b32_e32 v87, 8, v105
	v_cmp_gt_u32_e64 s[10:11], v104, v32
	v_cmp_gt_u32_e64 s[18:19], v144, v32
	s_add_i32 s43, s37, 0
	s_add_i32 s92, s51, 0x229c0
	s_add_i32 s86, s51, 0x22a00
	s_add_i32 s33, s51, 0x22a40
	s_add_i32 s50, s51, 0x22a80
	s_add_i32 s51, s51, 0x22ac0
	v_writelane_b32 v238, s0, 58
	s_and_b32 s84, s46, 3
	v_or_b32_e32 v160, 0xfffffe00, v0
	s_movk_i32 s64, 0xe40
	s_lshl_b32 s65, s2, 2
	v_add_u32_e32 v167, 0x25700, v1
	v_mov_b32_e32 v168, 0x260
	v_add_u32_e32 v169, 0, v13
	v_add_u32_e32 v170, 0, v14
	v_add_u32_e32 v171, 0, v15
	v_add_u32_e32 v172, 0, v23
	v_add_u32_e32 v173, 0, v24
	v_add_u32_e32 v174, 0, v25
	v_add_u32_e32 v175, 0, v26
	v_add_u32_e32 v177, 0, v27
	v_add_u32_e32 v178, v20, v29
	v_add_u32_e32 v179, v34, v37
	v_add_u32_e32 v180, v34, v36
	v_add_u32_e32 v181, v39, v21
	v_add_u32_e32 v182, v44, v46
	v_add_u32_e32 v183, v44, v45
	v_add_u32_e32 v184, v22, v21
	v_add_u32_e32 v185, v11, v86
	v_add_u32_e32 v186, v16, v10
	v_mov_b32_e32 v10, v89
	v_mov_b32_e32 v11, v89
	v_mov_b32_e32 v12, v89
	v_mov_b32_e32 v13, v89
	v_add_u32_e32 v187, v20, v31
	v_add_u32_e32 v188, v20, v35
	v_add_u32_e32 v189, v20, v38
	v_add_u32_e32 v190, 0, v40
	v_add_u32_e32 v191, v20, v41
	v_add_u32_e32 v192, 0, v43
	v_add_u32_e32 v193, 0, v28
	s_mov_b32 s46, 0
	v_cmp_eq_u32_e64 s[34:35], 1, v18
	v_cmp_gt_u32_e64 s[36:37], v42, v32
	v_cmp_eq_u32_e64 s[38:39], 1, v30
	v_cmp_eq_u32_e64 s[40:41], 1, v33
	v_writelane_b32 v238, s1, 59
	s_lshl_b32 s100, s84, 6
	s_or_b32 s100, s52, s100
	s_mov_b32 s101, s53
	v_lshl_add_u64 v[228:229], s[100:101], 0, v[90:91]
	v_mad_u64_u32 v[230:231], s[100:101], v228, s64, v[94:95]
	v_mad_i32_i24 v231, v229, s64, v231
	v_lshlrev_b64 v[228:229], 10, v[228:229]
	v_lshl_add_u64 v[232:233], v[96:97], 0, v[228:229]
	global_load_dwordx4 v[200:203], v[230:231], off
	global_load_dwordx4 v[204:207], v[230:231], off offset:1024
	global_load_dwordx4 v[208:211], v[230:231], off offset:2048
	v_or_b32_e32 v234, s84, v90
	v_cmp_ne_u32_e32 vcc, 0, v234
	v_mov_b32_e32 v212, v89
	v_mov_b32_e32 v213, v89
	v_mov_b32_e32 v214, v89
	v_mov_b32_e32 v215, v89
	v_mov_b32_e32 v216, v89
	v_mov_b32_e32 v217, v89
	v_mov_b32_e32 v218, v89
	v_mov_b32_e32 v219, v89
	v_mov_b32_e32 v220, v89
	v_mov_b32_e32 v221, v89
	v_mov_b32_e32 v222, v89
	v_mov_b32_e32 v223, v89
	s_and_saveexec_b64 s[100:101], vcc
	s_cbranch_execz .Lrc_p0
	global_load_dwordx4 v[212:215], v[230:231], off offset:-3648
	global_load_dwordx4 v[216:219], v[230:231], off offset:-2624
	global_load_dwordx4 v[220:223], v[230:231], off offset:-1600
.Lrc_p0:
	s_or_b64 exec, exec, s[100:101]
	global_load_dwordx4 v[224:227], v[232:233], off
	s_branch .LBB0_1035

.LBB0_1107:
	s_mov_b32 s2, 4
	v_mov_b32_e32 v1, v166
	v_mov_b32_e32 v22, v165
	v_mov_b32_e32 v23, v164
	v_mov_b32_e32 v24, v163
	v_mov_b32_e32 v25, v162
	v_mov_b32_e32 v26, v159
	s_waitcnt lgkmcnt(0)
	s_barrier
	s_cmp_eq_u32 s46, 15
	s_cbranch_scc1 .Lrc_nopf
	s_add_i32 s100, s46, 1
	s_lshl_b32 s100, s100, 2
	s_or_b32 s100, s84, s100
	s_lshl_b32 s100, s100, 6
	s_or_b32 s100, s52, s100
	s_mov_b32 s101, s53
	v_lshl_add_u64 v[228:229], s[100:101], 0, v[90:91]
	v_mad_u64_u32 v[230:231], s[100:101], v228, s64, v[94:95]
	v_mad_i32_i24 v231, v229, s64, v231
	v_lshlrev_b64 v[228:229], 10, v[228:229]
	v_lshl_add_u64 v[232:233], v[96:97], 0, v[228:229]
	global_load_dwordx4 v[200:203], v[230:231], off
	global_load_dwordx4 v[204:207], v[230:231], off offset:1024
	global_load_dwordx4 v[208:211], v[230:231], off offset:2048
	global_load_dwordx4 v[212:215], v[230:231], off offset:-3648
	global_load_dwordx4 v[216:219], v[230:231], off offset:-2624
	global_load_dwordx4 v[220:223], v[230:231], off offset:-1600
	global_load_dwordx4 v[224:227], v[232:233], off

.LBB0_1511:
	s_mov_b32 s99, -1
	s_cmp_lt_i32 s82, 13
	s_cselect_b64 s[4:5], -1, 0
	s_and_b64 s[4:5], s[4:5], s[0:1]
	s_andn2_b64 vcc, exec, s[4:5]
	s_cbranch_vccnz .LBB0_1528
	s_cmpk_gt_i32 s86, 0xaff
	v_readfirstlane_b32 s1, v0
	s_cbranch_scc1 .LBB0_1528
	s_waitcnt vmcnt(0)
	v_lshrrev_b32_e32 v1, 5, v0
	v_lshrrev_b32_e32 v3, 1, v0
	v_and_b32_e32 v1, 4, v1
	v_bfe_u32 v2, v0, 2, 2
	v_and_b32_e32 v3, 24, v3
	s_add_u32 s2, s80, 0xa900000
	v_or3_b32 v1, v1, v2, v3
	v_lshlrev_b32_e32 v2, 4, v0
	s_addc_u32 s30, s81, 0
	v_or_b32_e32 v10, 0x2000, v2
	s_add_u32 s31, s80, 0xd00000
	v_lshrrev_b32_e32 v3, 7, v10
	s_movk_i32 s0, 0x60
	s_addc_u32 s33, s81, 0
	v_and_or_b32 v4, v3, s0, v1
	v_bfe_u32 v13, v0, 2, 4
	s_movk_i32 s0, 0x70
	s_ashr_i32 s35, s86, 31
	v_and_or_b32 v3, v3, s0, v13
	s_lshr_b32 s0, s35, 29
	s_add_i32 s0, s86, s0
	s_lshr_b32 s10, s1, 6
	s_ashr_i32 s6, s0, 3
	s_and_b32 s0, s0, -8
	s_lshr_b32 s12, s1, 8
	s_lshl_b32 s34, s10, 10
	s_sub_i32 s0, s86, s0
	s_cmp_lt_i32 s0, 0
	s_movk_i32 s36, 0x161
	s_cselect_b32 s7, s36, 0x160
	s_mul_i32 s0, s7, s0
	s_add_i32 s0, s0, s6
	s_mul_hi_i32 s6, s0, 0x2e8ba2e9
	s_lshr_b32 s7, s6, 31
	s_ashr_i32 s6, s6, 5
	s_add_i32 s6, s6, s7
	s_lshl_b32 s7, s6, 3
	s_mulk_i32 s6, 0xb0
	s_sub_i32 s6, s0, s6
	s_sext_i32_i16 s0, s6
	s_bfe_u32 s0, s0, 0x3001c
	s_add_i32 s8, s6, s0
	s_sext_i32_i16 s0, s8
	s_and_b32 s8, s8, 0xfff8
	s_sub_i32 s6, s6, s8
	s_sext_i32_i16 s6, s6
	v_and_b32_e32 v5, 32, v0
	s_lshr_b32 s0, s0, 3
	s_add_i32 s22, s7, s6
	v_bitop3_b32 v11, v2, v5, 48 bitop3:0x6c
	v_and_b32_e32 v12, 64, v0
	s_ashr_i32 s23, s22, 31
	s_bfe_i64 s[8:9], s[0:1], 0x100000
	v_or_b32_e32 v2, v11, v12
	s_lshl_b64 s[6:7], s[22:23], 19
	s_lshl_b64 s[8:9], s[8:9], 19
	v_lshl_or_b32 v156, v3, 11, v2
	v_lshrrev_b32_e32 v3, 3, v0
	s_add_u32 s26, s31, s8
	v_and_or_b32 v1, v3, 32, v1
	s_addc_u32 s27, s33, s9
	s_add_i32 s23, s34, 0
	v_lshl_or_b32 v158, v1, 11, v2
	s_add_i32 m0, s23, 0x10000
	v_lshl_or_b32 v154, v4, 11, v2
	global_load_lds_dwordx4 v158, s[26:27]
	s_add_i32 m0, s23, 0x12000
	s_add_u32 s8, s26, 0x40000
	global_load_lds_dwordx4 v154, s[26:27]
	s_addc_u32 s9, s27, 0
	s_add_i32 m0, s23, 0x14000
	v_and_or_b32 v1, v3, 48, v13
	global_load_lds_dwordx4 v158, s[8:9]
	s_add_i32 m0, s23, 0x16000
	s_add_u32 s24, s2, s6
	s_addc_u32 s25, s30, s7
	s_add_i32 s37, s23, 0x2000
	v_lshl_or_b32 v160, v1, 11, v2
	global_load_lds_dwordx4 v154, s[8:9]
	s_mov_b32 m0, s23
	s_add_u32 s6, s24, 0x40000
	global_load_lds_dwordx4 v160, s[24:25]
	s_mov_b32 m0, s37
	s_addc_u32 s7, s25, 0
	s_add_i32 s38, s23, 0x4000
	global_load_lds_dwordx4 v156, s[24:25]
	s_mov_b32 m0, s38
	s_add_i32 s39, s23, 0x6000
	global_load_lds_dwordx4 v160, s[6:7]
	s_mov_b32 m0, s39
	v_mov_b32_e32 v159, 0
	global_load_lds_dwordx4 v156, s[6:7]
	v_mov_b32_e32 v155, v159
	v_mov_b32_e32 v161, v159
	v_mov_b32_e32 v157, v159
	s_cmp_eq_u32 s12, 1
	s_mov_b32 s40, 0
	v_lshl_add_u64 v[8:9], s[26:27], 0, v[158:159]
	v_lshl_add_u64 v[6:7], s[26:27], 0, v[154:155]
	v_lshl_add_u64 v[2:3], s[24:25], 0, v[160:161]
	s_cselect_b64 s[6:7], -1, 0
	s_cmp_lg_u32 s12, 1
	v_lshl_add_u64 v[4:5], s[24:25], 0, v[156:157]
	s_cbranch_scc1 .LBB0_1515
	s_barrier

.LBB0_1524:
	v_lshl_add_u32 v202, s22, 8, v1
	v_ashrrev_i32_e32 v203, 31, v202
	v_lshlrev_b64 v[130:131], 6, v[202:203]
	v_lshl_add_u64 v[130:131], v[162:163], 0, v[130:131]
	s_cmp_eq_u32 s22, s99
	s_cbranch_scc1 .Lp5c_a
	global_load_dwordx4 v[194:197], v[130:131], off
.Lp5c_a:
	v_or_b32_e32 v186, 16, v202
	v_or_b32_e32 v184, 32, v202
	v_or_b32_e32 v182, 48, v202
	v_add_u32_e32 v180, 0x80, v202
	v_add_u32_e32 v178, 0x90, v202
	v_add_u32_e32 v174, 0xa0, v202
	v_add_u32_e32 v172, 0xb0, v202
	v_ashrrev_i32_e32 v187, 31, v186
	v_ashrrev_i32_e32 v185, 31, v184
	v_ashrrev_i32_e32 v183, 31, v182
	v_ashrrev_i32_e32 v181, 31, v180
	v_ashrrev_i32_e32 v179, 31, v178
	v_ashrrev_i32_e32 v175, 31, v174
	v_ashrrev_i32_e32 v173, 31, v172
	v_lshlrev_b64 v[130:131], 6, v[186:187]
	v_lshlrev_b64 v[132:133], 6, v[184:185]
	v_lshlrev_b64 v[134:135], 6, v[182:183]
	v_lshlrev_b64 v[136:137], 6, v[180:181]
	v_lshlrev_b64 v[138:139], 6, v[178:179]
	v_lshlrev_b64 v[140:141], 6, v[174:175]
	v_lshlrev_b64 v[142:143], 6, v[172:173]
	v_lshl_add_u64 v[130:131], v[162:163], 0, v[130:131]
	v_lshl_add_u64 v[132:133], v[162:163], 0, v[132:133]
	v_lshl_add_u64 v[134:135], v[162:163], 0, v[134:135]
	v_lshl_add_u64 v[136:137], v[162:163], 0, v[136:137]
	v_lshl_add_u64 v[138:139], v[162:163], 0, v[138:139]
	v_lshl_add_u64 v[176:177], v[162:163], 0, v[140:141]
	v_lshl_add_u64 v[204:205], v[162:163], 0, v[142:143]
	s_cmp_eq_u32 s22, s99
	s_cbranch_scc1 .Lp5c_hit
	global_load_dwordx4 v[198:201], v[130:131], off
	global_load_dwordx4 v[150:153], v[132:133], off
	global_load_dwordx4 v[146:149], v[134:135], off
	global_load_dwordx4 v[142:145], v[136:137], off
	s_nop 0
	global_load_dwordx4 v[138:141], v[138:139], off
	s_nop 0
	global_load_dwordx4 v[134:137], v[176:177], off
	global_load_dwordx4 v[130:133], v[204:205], off
	s_mov_b32 s99, s22
	s_waitcnt vmcnt(0)
	s_branch .Lp5c_go
.Lp5c_hit:
	v_mul_f32_e32 v194, 0x3e800000, v240
	v_mov_b32_e32 v195, 0
	v_mov_b32_e32 v196, 0
	v_mov_b32_e32 v197, 0
	v_mul_f32_e32 v198, 0x3e800000, v241
	v_mov_b32_e32 v199, 0
	v_mov_b32_e32 v200, 0
	v_mov_b32_e32 v201, 0
	v_mul_f32_e32 v150, 0x3e800000, v242
	v_mov_b32_e32 v151, 0
	v_mov_b32_e32 v152, 0
	v_mov_b32_e32 v153, 0
	v_mul_f32_e32 v146, 0x3e800000, v243
	v_mov_b32_e32 v147, 0
	v_mov_b32_e32 v148, 0
	v_mov_b32_e32 v149, 0
	v_mul_f32_e32 v142, 0x3e800000, v244
	v_mov_b32_e32 v143, 0
	v_mov_b32_e32 v144, 0
	v_mov_b32_e32 v145, 0
	v_mul_f32_e32 v138, 0x3e800000, v245
	v_mov_b32_e32 v139, 0
	v_mov_b32_e32 v140, 0
	v_mov_b32_e32 v141, 0
	v_mul_f32_e32 v134, 0x3e800000, v246
	v_mov_b32_e32 v135, 0
	v_mov_b32_e32 v136, 0
	v_mov_b32_e32 v137, 0
	v_mul_f32_e32 v130, 0x3e800000, v247
	v_mov_b32_e32 v131, 0
	v_mov_b32_e32 v132, 0
	v_mov_b32_e32 v133, 0
.Lp5c_go:
	v_mov_b64_e32 v[176:177], s[8:9]
	v_add_f32_e32 v173, v194, v195
	v_add_f32_e32 v175, v196, v197
	v_add_f32_e32 v173, v173, v175
	v_mov_b32_e32 v175, v173
	v_lshl_or_b32 v194, s48, 7, v189
	s_nop 0
	v_permlane16_swap_b32_e32 v173, v175
	v_add_f32_e32 v173, v173, v175
	v_mov_b32_e32 v175, v173
	v_ashrrev_i32_e32 v195, 31, v194
	s_nop 0
	v_permlane32_swap_b32_e32 v173, v175
	v_add_f32_e32 v173, v173, v175
	v_mov_b32_e32 v240, v173
	v_fmamk_f32 v173, v173, 0x3a800000, v193
	v_mul_f32_e32 v175, 0x4b800000, v173
	v_cmp_gt_f32_e32 vcc, s46, v173
	s_nop 1
	v_cndmask_b32_e32 v173, v173, v175, vcc
	v_rsq_f32_e32 v173, v173
	s_nop 0
	v_mul_f32_e32 v175, 0x45800000, v173
	v_cndmask_b32_e32 v196, v173, v175, vcc
	v_pk_mul_f32 v[126:127], v[126:127], v[196:197] op_sel_hi:[1,0]
	v_pk_mul_f32 v[128:129], v[128:129], v[196:197] op_sel_hi:[1,0]
	v_pk_mul_f32 v[122:123], v[122:123], v[196:197] op_sel_hi:[1,0]
	v_pk_mul_f32 v[124:125], v[124:125], v[196:197] op_sel_hi:[1,0]
	v_mul_f32_e32 v173, 0xbfb8aa3b, v126
	v_mul_f32_e32 v175, 0xbfb8aa3b, v127
	v_mul_f32_e32 v179, 0xbfb8aa3b, v128
	v_mul_f32_e32 v181, 0xbfb8aa3b, v129
	v_mul_f32_e32 v183, 0xbfb8aa3b, v122
	v_mul_f32_e32 v185, 0xbfb8aa3b, v123
	v_pk_mul_f32 v[118:119], v[118:119], v[196:197] op_sel_hi:[1,0]
	v_pk_mul_f32 v[120:121], v[120:121], v[196:197] op_sel_hi:[1,0]
	v_pk_mul_f32 v[114:115], v[114:115], v[196:197] op_sel_hi:[1,0]
	v_pk_mul_f32 v[116:117], v[116:117], v[196:197] op_sel_hi:[1,0]
	v_mul_f32_e32 v187, 0xbfb8aa3b, v124
	v_mul_f32_e32 v196, 0xbfb8aa3b, v125
	v_exp_f32_e32 v173, v173
	v_exp_f32_e32 v175, v175
	v_exp_f32_e32 v179, v179
	v_exp_f32_e32 v181, v181
	v_exp_f32_e32 v183, v183
	v_exp_f32_e32 v185, v185
	v_exp_f32_e32 v187, v187
	v_exp_f32_e32 v196, v196
	v_add_f32_e32 v173, 1.0, v173
	v_add_f32_e32 v175, 1.0, v175
	v_add_f32_e32 v179, 1.0, v179
	v_add_f32_e32 v181, 1.0, v181
	v_add_f32_e32 v183, 1.0, v183
	v_add_f32_e32 v185, 1.0, v185
	v_add_f32_e32 v187, 1.0, v187
	v_add_f32_e32 v203, 1.0, v196
	v_rcp_f32_e32 v196, v173
	v_rcp_f32_e32 v197, v175
	v_rcp_f32_e32 v204, v179
	v_rcp_f32_e32 v205, v181
	v_rcp_f32_e32 v206, v183
	v_rcp_f32_e32 v207, v185
	v_rcp_f32_e32 v208, v187
	v_rcp_f32_e32 v209, v203
	v_pk_mul_f32 v[126:127], v[126:127], v[196:197]
	v_pk_mul_f32 v[128:129], v[128:129], v[204:205]
	v_pk_mul_f32 v[122:123], v[122:123], v[206:207]
	v_pk_mul_f32 v[124:125], v[124:125], v[208:209]
	v_pk_mul_f32 v[118:119], v[118:119], v[126:127]
	v_pk_mul_f32 v[120:121], v[120:121], v[128:129]
	v_pk_mul_f32 v[114:115], v[114:115], v[122:123]
	v_pk_mul_f32 v[122:123], v[116:117], v[124:125]
	v_cvt_pk_bf16_f32 v116, v118, v119
	v_cvt_pk_bf16_f32 v117, v120, v121
	v_cvt_pk_bf16_f32 v118, v114, v115
	v_mad_i64_i32 v[120:121], s[24:25], v202, s47, v[176:177]
	v_lshlrev_b64 v[114:115], 1, v[194:195]
	v_cvt_pk_bf16_f32 v119, v122, v123
	v_lshl_add_u64 v[120:121], v[120:121], 0, v[114:115]
	global_store_dwordx4 v[120:121], v[116:119], off
	s_nop 1
	v_add_f32_e32 v116, v198, v199
	v_add_f32_e32 v117, v200, v201
	v_add_f32_e32 v116, v116, v117
	v_mov_b32_e32 v117, v116
	s_nop 1
	v_permlane16_swap_b32_e32 v116, v117
	v_add_f32_e32 v116, v116, v117
	v_mov_b32_e32 v117, v116
	s_nop 1
	v_permlane32_swap_b32_e32 v116, v117
	v_add_f32_e32 v116, v116, v117
	v_mov_b32_e32 v241, v116
	v_fmamk_f32 v116, v116, 0x3a800000, v193
	v_mul_f32_e32 v117, 0x4b800000, v116
	v_cmp_gt_f32_e32 vcc, s46, v116
	s_nop 1
	v_cndmask_b32_e32 v116, v116, v117, vcc
	v_rsq_f32_e32 v116, v116
	s_nop 0
	v_mul_f32_e32 v117, 0x45800000, v116
	v_cndmask_b32_e32 v116, v116, v117, vcc
	v_pk_mul_f32 v[110:111], v[110:111], v[116:117] op_sel_hi:[1,0]
	s_nop 0
	v_mul_f32_e32 v117, 0xbfb8aa3b, v110
	v_exp_f32_e32 v117, v117
	v_mul_f32_e32 v118, 0xbfb8aa3b, v111
	v_exp_f32_e32 v119, v118
	v_add_f32_e32 v117, 1.0, v117
	v_rcp_f32_e32 v118, v117
	v_add_f32_e32 v117, 1.0, v119
	v_pk_mul_f32 v[112:113], v[112:113], v[116:117] op_sel_hi:[1,0]
	s_nop 0
	v_mul_f32_e32 v119, 0xbfb8aa3b, v112
	v_exp_f32_e32 v120, v119
	v_mul_f32_e32 v119, 0xbfb8aa3b, v113
	v_exp_f32_e32 v121, v119
	v_rcp_f32_e32 v119, v117
	v_add_f32_e32 v117, 1.0, v120
	v_rcp_f32_e32 v120, v117
	v_add_f32_e32 v117, 1.0, v121
	v_rcp_f32_e32 v121, v117
	v_pk_mul_f32 v[110:111], v[110:111], v[118:119]
	v_pk_mul_f32 v[102:103], v[102:103], v[116:117] op_sel_hi:[1,0]
	v_pk_mul_f32 v[106:107], v[106:107], v[116:117] op_sel_hi:[1,0]
	v_pk_mul_f32 v[102:103], v[102:103], v[110:111]
	v_pk_mul_f32 v[110:111], v[112:113], v[120:121]
	v_mul_f32_e32 v112, 0xbfb8aa3b, v106
	v_mul_f32_e32 v113, 0xbfb8aa3b, v107
	v_exp_f32_e32 v112, v112
	v_exp_f32_e32 v113, v113
	v_pk_mul_f32 v[104:105], v[104:105], v[116:117] op_sel_hi:[1,0]
	v_pk_mul_f32 v[108:109], v[108:109], v[116:117] op_sel_hi:[1,0]
	v_pk_mul_f32 v[104:105], v[104:105], v[110:111]
	v_add_f32_e32 v110, 1.0, v112
	v_add_f32_e32 v111, 1.0, v113
	v_mul_f32_e32 v112, 0xbfb8aa3b, v108
	v_mul_f32_e32 v113, 0xbfb8aa3b, v109
	v_exp_f32_e32 v112, v112
	v_exp_f32_e32 v113, v113
	v_rcp_f32_e32 v110, v110
	v_rcp_f32_e32 v111, v111
	v_add_f32_e32 v112, 1.0, v112
	v_add_f32_e32 v113, 1.0, v113
	v_rcp_f32_e32 v112, v112
	v_rcp_f32_e32 v113, v113
	v_pk_mul_f32 v[106:107], v[106:107], v[110:111]
	v_pk_mul_f32 v[98:99], v[98:99], v[116:117] op_sel_hi:[1,0]
	v_pk_mul_f32 v[100:101], v[100:101], v[116:117] op_sel_hi:[1,0]
	v_pk_mul_f32 v[106:107], v[98:99], v[106:107]
	v_pk_mul_f32 v[98:99], v[108:109], v[112:113]
	s_nop 0
	v_pk_mul_f32 v[108:109], v[100:101], v[98:99]
	v_cvt_pk_bf16_f32 v98, v102, v103
	v_mad_i64_i32 v[102:103], s[24:25], v186, s47, v[176:177]
	v_cvt_pk_bf16_f32 v99, v104, v105
	v_cvt_pk_bf16_f32 v100, v106, v107
	v_cvt_pk_bf16_f32 v101, v108, v109
	v_lshl_add_u64 v[102:103], v[102:103], 0, v[114:115]
	global_store_dwordx4 v[102:103], v[98:101], off
	s_nop 1
	v_add_f32_e32 v98, v150, v151
	v_add_f32_e32 v99, v152, v153
	v_add_f32_e32 v98, v98, v99
	v_mov_b32_e32 v99, v98
	s_nop 1
	v_permlane16_swap_b32_e32 v98, v99
	v_add_f32_e32 v98, v98, v99
	v_mov_b32_e32 v99, v98
	s_nop 1
	v_permlane32_swap_b32_e32 v98, v99
	v_add_f32_e32 v98, v98, v99
	v_mov_b32_e32 v242, v98
	v_fmamk_f32 v98, v98, 0x3a800000, v193
	v_mul_f32_e32 v99, 0x4b800000, v98
	v_cmp_gt_f32_e32 vcc, s46, v98
	s_nop 1
	v_cndmask_b32_e32 v98, v98, v99, vcc
	v_rsq_f32_e32 v98, v98
	s_nop 0
	v_mul_f32_e32 v99, 0x45800000, v98
	v_cndmask_b32_e32 v98, v98, v99, vcc
	v_pk_mul_f32 v[94:95], v[94:95], v[98:99] op_sel_hi:[1,0]
	s_nop 0
	v_mul_f32_e32 v99, 0xbfb8aa3b, v94
	v_exp_f32_e32 v99, v99
	v_mul_f32_e32 v100, 0xbfb8aa3b, v95
	v_exp_f32_e32 v101, v100
	v_add_f32_e32 v99, 1.0, v99
	v_rcp_f32_e32 v100, v99
	v_add_f32_e32 v99, 1.0, v101
	v_pk_mul_f32 v[96:97], v[96:97], v[98:99] op_sel_hi:[1,0]
	s_nop 0
	v_mul_f32_e32 v101, 0xbfb8aa3b, v96
	v_exp_f32_e32 v102, v101
	v_mul_f32_e32 v101, 0xbfb8aa3b, v97
	v_exp_f32_e32 v103, v101
	v_rcp_f32_e32 v101, v99
	v_add_f32_e32 v99, 1.0, v102
	v_rcp_f32_e32 v102, v99
	v_add_f32_e32 v99, 1.0, v103
	v_rcp_f32_e32 v103, v99
	v_pk_mul_f32 v[94:95], v[94:95], v[100:101]
	v_pk_mul_f32 v[86:87], v[86:87], v[98:99] op_sel_hi:[1,0]
	v_pk_mul_f32 v[90:91], v[90:91], v[98:99] op_sel_hi:[1,0]
	v_pk_mul_f32 v[86:87], v[86:87], v[94:95]
	v_pk_mul_f32 v[94:95], v[96:97], v[102:103]
	v_mul_f32_e32 v96, 0xbfb8aa3b, v90
	v_mul_f32_e32 v97, 0xbfb8aa3b, v91
	v_exp_f32_e32 v96, v96
	v_exp_f32_e32 v97, v97
	v_pk_mul_f32 v[88:89], v[88:89], v[98:99] op_sel_hi:[1,0]
	v_pk_mul_f32 v[92:93], v[92:93], v[98:99] op_sel_hi:[1,0]
	v_pk_mul_f32 v[88:89], v[88:89], v[94:95]
	v_add_f32_e32 v94, 1.0, v96
	v_add_f32_e32 v95, 1.0, v97
	v_mul_f32_e32 v96, 0xbfb8aa3b, v92
	v_mul_f32_e32 v97, 0xbfb8aa3b, v93
	v_exp_f32_e32 v96, v96
	v_exp_f32_e32 v97, v97
	v_rcp_f32_e32 v94, v94
	v_rcp_f32_e32 v95, v95
	v_add_f32_e32 v96, 1.0, v96
	v_add_f32_e32 v97, 1.0, v97
	v_rcp_f32_e32 v96, v96
	v_rcp_f32_e32 v97, v97
	v_pk_mul_f32 v[90:91], v[90:91], v[94:95]
	v_pk_mul_f32 v[82:83], v[82:83], v[98:99] op_sel_hi:[1,0]
	v_pk_mul_f32 v[84:85], v[84:85], v[98:99] op_sel_hi:[1,0]
	v_pk_mul_f32 v[90:91], v[82:83], v[90:91]
	v_pk_mul_f32 v[82:83], v[92:93], v[96:97]
	s_nop 0
	v_pk_mul_f32 v[92:93], v[84:85], v[82:83]
	v_cvt_pk_bf16_f32 v82, v86, v87
	v_mad_i64_i32 v[86:87], s[24:25], v184, s47, v[176:177]
	v_cvt_pk_bf16_f32 v83, v88, v89
	v_cvt_pk_bf16_f32 v84, v90, v91
	v_cvt_pk_bf16_f32 v85, v92, v93
	v_lshl_add_u64 v[86:87], v[86:87], 0, v[114:115]
	global_store_dwordx4 v[86:87], v[82:85], off
	s_nop 1
	v_add_f32_e32 v82, v146, v147
	v_add_f32_e32 v83, v148, v149
	v_add_f32_e32 v82, v82, v83
	v_mov_b32_e32 v83, v82
	s_nop 1
	v_permlane16_swap_b32_e32 v82, v83
	v_add_f32_e32 v82, v82, v83
	v_mov_b32_e32 v83, v82
	s_nop 1
	v_permlane32_swap_b32_e32 v82, v83
	v_add_f32_e32 v82, v82, v83
	v_mov_b32_e32 v243, v82
	v_fmamk_f32 v82, v82, 0x3a800000, v193
	v_mul_f32_e32 v83, 0x4b800000, v82
	v_cmp_gt_f32_e32 vcc, s46, v82
	s_nop 1
	v_cndmask_b32_e32 v82, v82, v83, vcc
	v_rsq_f32_e32 v82, v82
	s_nop 0
	v_mul_f32_e32 v83, 0x45800000, v82
	v_cndmask_b32_e32 v82, v82, v83, vcc
	v_pk_mul_f32 v[78:79], v[78:79], v[82:83] op_sel_hi:[1,0]
	s_nop 0
	v_mul_f32_e32 v83, 0xbfb8aa3b, v78
	v_exp_f32_e32 v83, v83
	v_mul_f32_e32 v84, 0xbfb8aa3b, v79
	v_exp_f32_e32 v85, v84
	v_add_f32_e32 v83, 1.0, v83
	v_rcp_f32_e32 v84, v83
	v_add_f32_e32 v83, 1.0, v85
	v_pk_mul_f32 v[80:81], v[80:81], v[82:83] op_sel_hi:[1,0]
	s_nop 0
	v_mul_f32_e32 v85, 0xbfb8aa3b, v80
	v_exp_f32_e32 v86, v85
	v_mul_f32_e32 v85, 0xbfb8aa3b, v81
	v_exp_f32_e32 v87, v85
	v_rcp_f32_e32 v85, v83
	v_add_f32_e32 v83, 1.0, v86
	v_rcp_f32_e32 v86, v83
	v_add_f32_e32 v83, 1.0, v87
	v_rcp_f32_e32 v87, v83
	v_pk_mul_f32 v[78:79], v[78:79], v[84:85]
	v_pk_mul_f32 v[70:71], v[70:71], v[82:83] op_sel_hi:[1,0]
	v_pk_mul_f32 v[74:75], v[74:75], v[82:83] op_sel_hi:[1,0]
	v_pk_mul_f32 v[70:71], v[70:71], v[78:79]
	v_pk_mul_f32 v[78:79], v[80:81], v[86:87]
	v_mul_f32_e32 v80, 0xbfb8aa3b, v74
	v_mul_f32_e32 v81, 0xbfb8aa3b, v75
	v_exp_f32_e32 v80, v80
	v_exp_f32_e32 v81, v81
	v_pk_mul_f32 v[72:73], v[72:73], v[82:83] op_sel_hi:[1,0]
	v_pk_mul_f32 v[76:77], v[76:77], v[82:83] op_sel_hi:[1,0]
	v_pk_mul_f32 v[72:73], v[72:73], v[78:79]
	v_add_f32_e32 v78, 1.0, v80
	v_add_f32_e32 v79, 1.0, v81
	v_mul_f32_e32 v80, 0xbfb8aa3b, v76
	v_mul_f32_e32 v81, 0xbfb8aa3b, v77
	v_exp_f32_e32 v80, v80
	v_exp_f32_e32 v81, v81
	v_rcp_f32_e32 v78, v78
	v_rcp_f32_e32 v79, v79
	v_add_f32_e32 v80, 1.0, v80
	v_add_f32_e32 v81, 1.0, v81
	v_rcp_f32_e32 v80, v80
	v_rcp_f32_e32 v81, v81
	v_pk_mul_f32 v[74:75], v[74:75], v[78:79]
	v_pk_mul_f32 v[66:67], v[66:67], v[82:83] op_sel_hi:[1,0]
	v_pk_mul_f32 v[68:69], v[68:69], v[82:83] op_sel_hi:[1,0]
	v_pk_mul_f32 v[74:75], v[66:67], v[74:75]
	v_pk_mul_f32 v[66:67], v[76:77], v[80:81]
	s_nop 0
	v_pk_mul_f32 v[76:77], v[68:69], v[66:67]
	v_cvt_pk_bf16_f32 v66, v70, v71
	v_mad_i64_i32 v[70:71], s[24:25], v182, s47, v[176:177]
	v_cvt_pk_bf16_f32 v67, v72, v73
	v_cvt_pk_bf16_f32 v68, v74, v75
	v_cvt_pk_bf16_f32 v69, v76, v77
	v_lshl_add_u64 v[70:71], v[70:71], 0, v[114:115]
	global_store_dwordx4 v[70:71], v[66:69], off
	s_nop 1
	v_add_f32_e32 v66, v142, v143
	v_add_f32_e32 v67, v144, v145
	v_add_f32_e32 v66, v66, v67
	v_mov_b32_e32 v67, v66
	s_nop 1
	v_permlane16_swap_b32_e32 v66, v67
	v_add_f32_e32 v66, v66, v67
	v_mov_b32_e32 v67, v66
	s_nop 1
	v_permlane32_swap_b32_e32 v66, v67
	v_add_f32_e32 v66, v66, v67
	v_mov_b32_e32 v244, v66
	v_fmamk_f32 v66, v66, 0x3a800000, v193
	v_mul_f32_e32 v67, 0x4b800000, v66
	v_cmp_gt_f32_e32 vcc, s46, v66
	s_nop 1
	v_cndmask_b32_e32 v66, v66, v67, vcc
	v_rsq_f32_e32 v66, v66
	s_nop 0
	v_mul_f32_e32 v67, 0x45800000, v66
	v_cndmask_b32_e32 v66, v66, v67, vcc
	v_pk_mul_f32 v[62:63], v[62:63], v[66:67] op_sel_hi:[1,0]
	s_nop 0
	v_mul_f32_e32 v67, 0xbfb8aa3b, v62
	v_exp_f32_e32 v67, v67
	v_mul_f32_e32 v68, 0xbfb8aa3b, v63
	v_exp_f32_e32 v69, v68
	v_add_f32_e32 v67, 1.0, v67
	v_rcp_f32_e32 v68, v67
	v_add_f32_e32 v67, 1.0, v69
	v_pk_mul_f32 v[64:65], v[64:65], v[66:67] op_sel_hi:[1,0]
	s_nop 0
	v_mul_f32_e32 v69, 0xbfb8aa3b, v64
	v_exp_f32_e32 v70, v69
	v_mul_f32_e32 v69, 0xbfb8aa3b, v65
	v_exp_f32_e32 v71, v69
	v_rcp_f32_e32 v69, v67
	v_add_f32_e32 v67, 1.0, v70
	v_rcp_f32_e32 v70, v67
	v_add_f32_e32 v67, 1.0, v71
	v_rcp_f32_e32 v71, v67
	v_pk_mul_f32 v[62:63], v[62:63], v[68:69]
	v_pk_mul_f32 v[54:55], v[54:55], v[66:67] op_sel_hi:[1,0]
	v_pk_mul_f32 v[58:59], v[58:59], v[66:67] op_sel_hi:[1,0]
	v_pk_mul_f32 v[54:55], v[54:55], v[62:63]
	v_pk_mul_f32 v[62:63], v[64:65], v[70:71]
	v_mul_f32_e32 v64, 0xbfb8aa3b, v58
	v_mul_f32_e32 v65, 0xbfb8aa3b, v59
	v_exp_f32_e32 v64, v64
	v_exp_f32_e32 v65, v65
	v_pk_mul_f32 v[56:57], v[56:57], v[66:67] op_sel_hi:[1,0]
	v_pk_mul_f32 v[60:61], v[60:61], v[66:67] op_sel_hi:[1,0]
	v_pk_mul_f32 v[56:57], v[56:57], v[62:63]
	v_add_f32_e32 v62, 1.0, v64
	v_add_f32_e32 v63, 1.0, v65
	v_mul_f32_e32 v64, 0xbfb8aa3b, v60
	v_mul_f32_e32 v65, 0xbfb8aa3b, v61
	v_exp_f32_e32 v64, v64
	v_exp_f32_e32 v65, v65
	v_rcp_f32_e32 v62, v62
	v_rcp_f32_e32 v63, v63
	v_add_f32_e32 v64, 1.0, v64
	v_add_f32_e32 v65, 1.0, v65
	v_rcp_f32_e32 v64, v64
	v_rcp_f32_e32 v65, v65
	v_pk_mul_f32 v[58:59], v[58:59], v[62:63]
	v_pk_mul_f32 v[50:51], v[50:51], v[66:67] op_sel_hi:[1,0]
	v_pk_mul_f32 v[52:53], v[52:53], v[66:67] op_sel_hi:[1,0]
	v_pk_mul_f32 v[58:59], v[50:51], v[58:59]
	v_pk_mul_f32 v[50:51], v[60:61], v[64:65]
	s_nop 0
	v_pk_mul_f32 v[60:61], v[52:53], v[50:51]
	v_cvt_pk_bf16_f32 v50, v54, v55
	v_mad_i64_i32 v[54:55], s[24:25], v180, s47, v[176:177]
	v_cvt_pk_bf16_f32 v51, v56, v57
	v_cvt_pk_bf16_f32 v52, v58, v59
	v_cvt_pk_bf16_f32 v53, v60, v61
	v_lshl_add_u64 v[54:55], v[54:55], 0, v[114:115]
	global_store_dwordx4 v[54:55], v[50:53], off
	s_nop 1
	v_add_f32_e32 v50, v138, v139
	v_add_f32_e32 v51, v140, v141
	v_add_f32_e32 v50, v50, v51
	v_mov_b32_e32 v51, v50
	s_nop 1
	v_permlane16_swap_b32_e32 v50, v51
	v_add_f32_e32 v50, v50, v51
	v_mov_b32_e32 v51, v50
	s_nop 1
	v_permlane32_swap_b32_e32 v50, v51
	v_add_f32_e32 v50, v50, v51
	v_mov_b32_e32 v245, v50
	v_fmamk_f32 v50, v50, 0x3a800000, v193
	v_mul_f32_e32 v51, 0x4b800000, v50
	v_cmp_gt_f32_e32 vcc, s46, v50
	s_nop 1
	v_cndmask_b32_e32 v50, v50, v51, vcc
	v_rsq_f32_e32 v50, v50
	s_nop 0
	v_mul_f32_e32 v51, 0x45800000, v50
	v_cndmask_b32_e32 v50, v50, v51, vcc
	v_pk_mul_f32 v[46:47], v[46:47], v[50:51] op_sel_hi:[1,0]
	s_nop 0
	v_mul_f32_e32 v51, 0xbfb8aa3b, v46
	v_exp_f32_e32 v51, v51
	v_mul_f32_e32 v52, 0xbfb8aa3b, v47
	v_exp_f32_e32 v53, v52
	v_add_f32_e32 v51, 1.0, v51
	v_rcp_f32_e32 v52, v51
	v_add_f32_e32 v51, 1.0, v53
	v_pk_mul_f32 v[48:49], v[48:49], v[50:51] op_sel_hi:[1,0]
	s_nop 0
	v_mul_f32_e32 v53, 0xbfb8aa3b, v48
	v_exp_f32_e32 v54, v53
	v_mul_f32_e32 v53, 0xbfb8aa3b, v49
	v_exp_f32_e32 v55, v53
	v_rcp_f32_e32 v53, v51
	v_add_f32_e32 v51, 1.0, v54
	v_rcp_f32_e32 v54, v51
	v_add_f32_e32 v51, 1.0, v55
	v_rcp_f32_e32 v55, v51
	v_pk_mul_f32 v[46:47], v[46:47], v[52:53]
	v_pk_mul_f32 v[38:39], v[38:39], v[50:51] op_sel_hi:[1,0]
	v_pk_mul_f32 v[42:43], v[42:43], v[50:51] op_sel_hi:[1,0]
	v_pk_mul_f32 v[38:39], v[38:39], v[46:47]
	v_pk_mul_f32 v[46:47], v[48:49], v[54:55]
	v_mul_f32_e32 v48, 0xbfb8aa3b, v42
	v_mul_f32_e32 v49, 0xbfb8aa3b, v43
	v_exp_f32_e32 v48, v48
	v_exp_f32_e32 v49, v49
	v_pk_mul_f32 v[40:41], v[40:41], v[50:51] op_sel_hi:[1,0]
	v_pk_mul_f32 v[44:45], v[44:45], v[50:51] op_sel_hi:[1,0]
	v_pk_mul_f32 v[40:41], v[40:41], v[46:47]
	v_add_f32_e32 v46, 1.0, v48
	v_add_f32_e32 v47, 1.0, v49
	v_mul_f32_e32 v48, 0xbfb8aa3b, v44
	v_mul_f32_e32 v49, 0xbfb8aa3b, v45
	v_exp_f32_e32 v48, v48
	v_exp_f32_e32 v49, v49
	v_rcp_f32_e32 v46, v46
	v_rcp_f32_e32 v47, v47
	v_add_f32_e32 v48, 1.0, v48
	v_add_f32_e32 v49, 1.0, v49
	v_rcp_f32_e32 v48, v48
	v_rcp_f32_e32 v49, v49
	v_pk_mul_f32 v[42:43], v[42:43], v[46:47]
	v_pk_mul_f32 v[34:35], v[34:35], v[50:51] op_sel_hi:[1,0]
	v_pk_mul_f32 v[36:37], v[36:37], v[50:51] op_sel_hi:[1,0]
	v_pk_mul_f32 v[42:43], v[34:35], v[42:43]
	v_pk_mul_f32 v[34:35], v[44:45], v[48:49]
	s_nop 0
	v_pk_mul_f32 v[44:45], v[36:37], v[34:35]
	v_cvt_pk_bf16_f32 v34, v38, v39
	v_mad_i64_i32 v[38:39], s[24:25], v178, s47, v[176:177]
	v_cvt_pk_bf16_f32 v35, v40, v41
	v_cvt_pk_bf16_f32 v36, v42, v43
	v_cvt_pk_bf16_f32 v37, v44, v45
	v_lshl_add_u64 v[38:39], v[38:39], 0, v[114:115]
	global_store_dwordx4 v[38:39], v[34:37], off
	s_nop 1
	v_add_f32_e32 v34, v134, v135
	v_add_f32_e32 v35, v136, v137
	v_add_f32_e32 v34, v34, v35
	v_mov_b32_e32 v35, v34
	s_nop 1
	v_permlane16_swap_b32_e32 v34, v35
	v_add_f32_e32 v34, v34, v35
	v_mov_b32_e32 v35, v34
	s_nop 1
	v_permlane32_swap_b32_e32 v34, v35
	v_add_f32_e32 v34, v34, v35
	v_mov_b32_e32 v246, v34
	v_fmamk_f32 v34, v34, 0x3a800000, v193
	v_mul_f32_e32 v35, 0x4b800000, v34
	v_cmp_gt_f32_e32 vcc, s46, v34
	s_nop 1
	v_cndmask_b32_e32 v34, v34, v35, vcc
	v_rsq_f32_e32 v34, v34
	s_nop 0
	v_mul_f32_e32 v35, 0x45800000, v34
	v_cndmask_b32_e32 v34, v34, v35, vcc
	v_pk_mul_f32 v[30:31], v[30:31], v[34:35] op_sel_hi:[1,0]
	s_nop 0
	v_mul_f32_e32 v35, 0xbfb8aa3b, v30
	v_exp_f32_e32 v35, v35
	v_mul_f32_e32 v36, 0xbfb8aa3b, v31
	v_exp_f32_e32 v37, v36
	v_add_f32_e32 v35, 1.0, v35
	v_rcp_f32_e32 v36, v35
	v_add_f32_e32 v35, 1.0, v37
	v_pk_mul_f32 v[32:33], v[32:33], v[34:35] op_sel_hi:[1,0]
	s_nop 0
	v_mul_f32_e32 v37, 0xbfb8aa3b, v32
	v_exp_f32_e32 v38, v37
	v_mul_f32_e32 v37, 0xbfb8aa3b, v33
	v_exp_f32_e32 v39, v37
	v_rcp_f32_e32 v37, v35
	v_add_f32_e32 v35, 1.0, v38
	v_rcp_f32_e32 v38, v35
	v_add_f32_e32 v35, 1.0, v39
	v_rcp_f32_e32 v39, v35
	v_pk_mul_f32 v[30:31], v[30:31], v[36:37]
	v_pk_mul_f32 v[22:23], v[22:23], v[34:35] op_sel_hi:[1,0]
	v_pk_mul_f32 v[26:27], v[26:27], v[34:35] op_sel_hi:[1,0]
	v_pk_mul_f32 v[22:23], v[22:23], v[30:31]
	v_pk_mul_f32 v[30:31], v[32:33], v[38:39]
	v_mul_f32_e32 v32, 0xbfb8aa3b, v26
	v_mul_f32_e32 v33, 0xbfb8aa3b, v27
	v_exp_f32_e32 v32, v32
	v_exp_f32_e32 v33, v33
	v_pk_mul_f32 v[24:25], v[24:25], v[34:35] op_sel_hi:[1,0]
	v_pk_mul_f32 v[28:29], v[28:29], v[34:35] op_sel_hi:[1,0]
	v_pk_mul_f32 v[24:25], v[24:25], v[30:31]
	v_add_f32_e32 v30, 1.0, v32
	v_add_f32_e32 v31, 1.0, v33
	v_mul_f32_e32 v32, 0xbfb8aa3b, v28
	v_mul_f32_e32 v33, 0xbfb8aa3b, v29
	v_exp_f32_e32 v32, v32
	v_exp_f32_e32 v33, v33
	v_rcp_f32_e32 v30, v30
	v_rcp_f32_e32 v31, v31
	v_add_f32_e32 v32, 1.0, v32
	v_add_f32_e32 v33, 1.0, v33
	v_rcp_f32_e32 v32, v32
	v_rcp_f32_e32 v33, v33
	v_pk_mul_f32 v[26:27], v[26:27], v[30:31]
	v_pk_mul_f32 v[18:19], v[18:19], v[34:35] op_sel_hi:[1,0]
	v_pk_mul_f32 v[20:21], v[20:21], v[34:35] op_sel_hi:[1,0]
	v_pk_mul_f32 v[26:27], v[18:19], v[26:27]
	v_pk_mul_f32 v[18:19], v[28:29], v[32:33]
	s_nop 0
	v_pk_mul_f32 v[28:29], v[20:21], v[18:19]
	v_cvt_pk_bf16_f32 v18, v22, v23
	v_mad_i64_i32 v[22:23], s[24:25], v174, s47, v[176:177]
	v_cvt_pk_bf16_f32 v19, v24, v25
	v_cvt_pk_bf16_f32 v20, v26, v27
	v_cvt_pk_bf16_f32 v21, v28, v29
	v_lshl_add_u64 v[22:23], v[22:23], 0, v[114:115]
	global_store_dwordx4 v[22:23], v[18:21], off
	s_nop 1
	v_add_f32_e32 v18, v130, v131
	v_add_f32_e32 v19, v132, v133
	v_add_f32_e32 v18, v18, v19
	v_mov_b32_e32 v19, v18
	s_nop 1
	v_permlane16_swap_b32_e32 v18, v19
	v_add_f32_e32 v18, v18, v19
	v_mov_b32_e32 v19, v18
	s_nop 1
	v_permlane32_swap_b32_e32 v18, v19
	v_add_f32_e32 v18, v18, v19
	v_mov_b32_e32 v247, v18
	v_fmamk_f32 v18, v18, 0x3a800000, v193
	v_mul_f32_e32 v19, 0x4b800000, v18
	v_cmp_gt_f32_e32 vcc, s46, v18
	s_nop 1
	v_cndmask_b32_e32 v18, v18, v19, vcc
	v_rsq_f32_e32 v18, v18
	s_nop 0
	v_mul_f32_e32 v19, 0x45800000, v18
	v_cndmask_b32_e32 v18, v18, v19, vcc
	v_pk_mul_f32 v[14:15], v[14:15], v[18:19] op_sel_hi:[1,0]
	s_andn2_b64 vcc, exec, s[0:1]
	v_mul_f32_e32 v19, 0xbfb8aa3b, v14
	v_exp_f32_e32 v19, v19
	v_mul_f32_e32 v20, 0xbfb8aa3b, v15
	v_exp_f32_e32 v21, v20
	s_mov_b64 s[0:1], -1
	v_add_f32_e32 v19, 1.0, v19
	v_rcp_f32_e32 v20, v19
	v_add_f32_e32 v19, 1.0, v21
	v_pk_mul_f32 v[16:17], v[16:17], v[18:19] op_sel_hi:[1,0]
	s_nop 0
	v_mul_f32_e32 v21, 0xbfb8aa3b, v16
	v_exp_f32_e32 v22, v21
	v_mul_f32_e32 v21, 0xbfb8aa3b, v17
	v_exp_f32_e32 v23, v21
	v_rcp_f32_e32 v21, v19
	v_add_f32_e32 v19, 1.0, v22
	v_rcp_f32_e32 v22, v19
	v_add_f32_e32 v19, 1.0, v23
	v_rcp_f32_e32 v23, v19
	v_pk_mul_f32 v[14:15], v[14:15], v[20:21]
	v_pk_mul_f32 v[6:7], v[6:7], v[18:19] op_sel_hi:[1,0]
	v_pk_mul_f32 v[10:11], v[10:11], v[18:19] op_sel_hi:[1,0]
	v_pk_mul_f32 v[6:7], v[6:7], v[14:15]
	v_pk_mul_f32 v[14:15], v[16:17], v[22:23]
	v_mul_f32_e32 v16, 0xbfb8aa3b, v10
	v_mul_f32_e32 v17, 0xbfb8aa3b, v11
	v_exp_f32_e32 v16, v16
	v_exp_f32_e32 v17, v17
	v_pk_mul_f32 v[8:9], v[8:9], v[18:19] op_sel_hi:[1,0]
	v_pk_mul_f32 v[12:13], v[12:13], v[18:19] op_sel_hi:[1,0]
	v_pk_mul_f32 v[8:9], v[8:9], v[14:15]
	v_add_f32_e32 v14, 1.0, v16
	v_add_f32_e32 v15, 1.0, v17
	v_mul_f32_e32 v16, 0xbfb8aa3b, v12
	v_mul_f32_e32 v17, 0xbfb8aa3b, v13
	v_exp_f32_e32 v16, v16
	v_exp_f32_e32 v17, v17
	v_rcp_f32_e32 v14, v14
	v_rcp_f32_e32 v15, v15
	v_add_f32_e32 v16, 1.0, v16
	v_add_f32_e32 v17, 1.0, v17
	v_rcp_f32_e32 v16, v16
	v_rcp_f32_e32 v17, v17
	v_pk_mul_f32 v[10:11], v[10:11], v[14:15]
	v_pk_mul_f32 v[2:3], v[2:3], v[18:19] op_sel_hi:[1,0]
	v_pk_mul_f32 v[4:5], v[4:5], v[18:19] op_sel_hi:[1,0]
	v_pk_mul_f32 v[10:11], v[2:3], v[10:11]
	v_pk_mul_f32 v[2:3], v[12:13], v[16:17]
	s_nop 0
	v_pk_mul_f32 v[12:13], v[4:5], v[2:3]
	v_cvt_pk_bf16_f32 v2, v6, v7
	v_mad_i64_i32 v[6:7], s[24:25], v172, s47, v[176:177]
	v_cvt_pk_bf16_f32 v3, v8, v9
	v_cvt_pk_bf16_f32 v4, v10, v11
	v_cvt_pk_bf16_f32 v5, v12, v13
	v_lshl_add_u64 v[6:7], v[6:7], 0, v[114:115]
	global_store_dwordx4 v[6:7], v[2:5], off
	s_cbranch_vccnz .LBB0_1517
	s_andn2_b64 vcc, exec, s[6:7]
	s_cbranch_vccnz .LBB0_1516
	s_barrier
	s_branch .LBB0_1516

	.amdhsa_kernel _Z4mega4Args
		.amdhsa_group_segment_fixed_size 0
		.amdhsa_private_segment_fixed_size 0
		.amdhsa_kernarg_size 464
		.amdhsa_user_sgpr_count 2
		.amdhsa_user_sgpr_dispatch_ptr 0
		.amdhsa_user_sgpr_queue_ptr 0
		.amdhsa_user_sgpr_kernarg_segment_ptr 1
		.amdhsa_user_sgpr_dispatch_id 0
		.amdhsa_user_sgpr_kernarg_preload_length 0
		.amdhsa_user_sgpr_kernarg_preload_offset 0
		.amdhsa_user_sgpr_private_segment_size 0
		.amdhsa_uses_dynamic_stack 0
		.amdhsa_enable_private_segment 0
		.amdhsa_system_sgpr_workgroup_id_x 1
		.amdhsa_system_sgpr_workgroup_id_y 0
		.amdhsa_system_sgpr_workgroup_id_z 0
		.amdhsa_system_sgpr_workgroup_info 0
		.amdhsa_system_vgpr_workitem_id 0
		.amdhsa_next_free_vgpr 256
		.amdhsa_next_free_sgpr 102
		.amdhsa_accum_offset 256
		.amdhsa_reserve_vcc 1
		.amdhsa_float_round_mode_32 0
		.amdhsa_float_round_mode_16_64 0
		.amdhsa_float_denorm_mode_32 3
		.amdhsa_float_denorm_mode_16_64 3
		.amdhsa_dx10_clamp 1
		.amdhsa_ieee_mode 1
		.amdhsa_fp16_overflow 0
		.amdhsa_tg_split 0
		.amdhsa_exception_fp_ieee_invalid_op 0
		.amdhsa_exception_fp_denorm_src 0
		.amdhsa_exception_fp_ieee_div_zero 0
		.amdhsa_exception_fp_ieee_overflow 0
		.amdhsa_exception_fp_ieee_underflow 0
		.amdhsa_exception_fp_ieee_inexact 0
		.amdhsa_exception_int_div_zero 0
	.end_amdhsa_kernel

amdhsa.kernels:
  - .agpr_count:     0
    .args:
      - .offset:         0
        .size:           208
        .value_kind:     by_value
      - .offset:         208
        .size:           4
        .value_kind:     hidden_block_count_x
      - .offset:         212
        .size:           4
        .value_kind:     hidden_block_count_y
      - .offset:         216
        .size:           4
        .value_kind:     hidden_block_count_z
      - .offset:         220
        .size:           2
        .value_kind:     hidden_group_size_x
      - .offset:         222
        .size:           2
        .value_kind:     hidden_group_size_y
      - .offset:         224
        .size:           2
        .value_kind:     hidden_group_size_z
      - .offset:         226
        .size:           2
        .value_kind:     hidden_remainder_x
      - .offset:         228
        .size:           2
        .value_kind:     hidden_remainder_y
      - .offset:         230
        .size:           2
        .value_kind:     hidden_remainder_z
      - .offset:         248
        .size:           8
        .value_kind:     hidden_global_offset_x
      - .offset:         256
        .size:           8
        .value_kind:     hidden_global_offset_y
      - .offset:         264
        .size:           8
        .value_kind:     hidden_global_offset_z
      - .offset:         272
        .size:           2
        .value_kind:     hidden_grid_dims
      - .offset:         328
        .size:           4
        .value_kind:     hidden_dynamic_lds_size
    .group_segment_fixed_size: 0
    .kernarg_segment_align: 8
    .kernarg_segment_size: 464
    .language:       OpenCL C
    .language_version:
      - 2
      - 0
    .max_flat_workgroup_size: 512
    .name:           _Z4mega4Args
    .private_segment_fixed_size: 0
    .sgpr_count:     108
    .sgpr_spill_count: 62
    .symbol:         _Z4mega4Args.kd
    .uniform_work_group_size: 1
    .uses_dynamic_stack: false
    .vgpr_count:     256
    .vgpr_spill_count: 0
    .wavefront_size: 64
